# speedup vs baseline: 1.0233x; 1.0233x over previous
.Lmy_w6_t1:
	s_waitcnt vmcnt(0)
	s_branch .LBB0_1235

.LBB0_1233:
	s_add_i32 s80, s66, -1
	s_cmpk_lt_u32 s80, 0x400
	v_add_u32_e32 v137, 16, v142
	v_add_u32_e32 v138, -16, v141
	v_add_u32_e32 v139, 17, v142
	v_subrev_u32_e32 v140, 17, v141
	v_add_u32_e32 v145, 18, v142
	v_subrev_u32_e32 v147, 18, v141
	v_add_u32_e32 v148, 19, v142
	v_subrev_u32_e32 v149, 19, v141
	v_add_u32_e32 v150, 20, v142
	v_subrev_u32_e32 v151, 20, v141
	v_add_u32_e32 v152, 21, v142
	v_subrev_u32_e32 v153, 21, v141
	s_cselect_b64 s[54:55], -1, 0
	s_cmpk_gt_u32 s80, 0x3ff
	v_cndmask_b32_e64 v144, v138, v137, s[0:1]
	v_cndmask_b32_e64 v143, v140, v139, s[0:1]
	v_cndmask_b32_e64 v140, v147, v145, s[0:1]
	v_cndmask_b32_e64 v139, v149, v148, s[0:1]
	v_cndmask_b32_e64 v138, v151, v150, s[0:1]
	v_cndmask_b32_e64 v137, v153, v152, s[0:1]
	s_cbranch_scc1 .Lmy_w6_t1
	s_waitcnt vmcnt(46)
	v_mul_lo_u32 v53, v144, s67
	v_cmp_lt_i32_e32 vcc, 0, v144
	v_add_lshl_u32 v53, v53, v6, 1
	v_add_u32_e32 v56, 0x800, v53
	v_cndmask_b32_e32 v54, 0, v26, vcc
	v_cmp_gt_i32_e32 vcc, s77, v144
	v_add_u32_e32 v54, v53, v54
	v_add_u32_e32 v57, 0xfffff800, v54
	v_cndmask_b32_e32 v55, 0, v27, vcc
	s_waitcnt vmcnt(38)
	v_add_u32_e32 v61, v53, v55
	v_add_u32_e32 v55, 0xfffff800, v53
	v_add_u32_e32 v62, 0x800, v54
	v_add_u32_e32 v63, 0xfffff800, v61
	global_load_ushort v60, v55, s[72:73]
	global_load_ushort v59, v53, s[72:73]
	global_load_ushort v58, v56, s[72:73]
	s_nop 0
	global_load_ushort v57, v57, s[72:73]
	s_nop 0
	global_load_ushort v56, v54, s[72:73]
	global_load_ushort v55, v62, s[72:73]
	s_nop 0
	global_load_ushort v54, v63, s[72:73]
	global_load_ushort v53, v61, s[72:73]
	v_mul_lo_u32 v62, v143, s67
	v_cmp_lt_i32_e32 vcc, 0, v143
	v_add_lshl_u32 v62, v62, v6, 1
	v_add_u32_e32 v61, 0x800, v61
	v_cndmask_b32_e32 v63, 0, v26, vcc
	v_cmp_gt_i32_e32 vcc, s77, v143
	v_add_u32_e32 v63, v62, v63
	v_add_u32_e32 v65, 0x800, v62
	v_cndmask_b32_e32 v64, 0, v27, vcc
	s_waitcnt vmcnt(38)
	v_add_u32_e32 v77, v62, v64
	v_add_u32_e32 v64, 0xfffff800, v62
	v_add_u32_e32 v78, 0xfffff800, v63
	v_add_u32_e32 v79, 0x800, v63
	global_load_ushort v68, v61, s[72:73]
	global_load_ushort v67, v64, s[72:73]
	global_load_ushort v66, v62, s[72:73]
	s_nop 0
	global_load_ushort v65, v65, s[72:73]
	s_nop 0
	global_load_ushort v64, v78, s[72:73]
	s_nop 0
	global_load_ushort v63, v63, s[72:73]
	s_nop 0
	global_load_ushort v62, v79, s[72:73]
	global_load_ushort v61, v77, s[72:73]
	v_mul_lo_u32 v78, v140, s67
	v_cmp_lt_i32_e32 vcc, 0, v140
	v_add_lshl_u32 v78, v78, v6, 1
	v_add_u32_e32 v80, 0xfffff800, v77
	v_cndmask_b32_e32 v79, 0, v26, vcc
	v_cmp_gt_i32_e32 vcc, s77, v140
	s_waitcnt vmcnt(38)
	v_add_u32_e32 v93, v78, v79
	v_add_u32_e32 v77, 0x800, v77
	v_cndmask_b32_e32 v79, 0, v27, vcc
	v_add_u32_e32 v94, v78, v79
	v_add_u32_e32 v79, 0xfffff800, v78
	v_add_u32_e32 v95, 0x800, v78
	v_add_u32_e32 v96, 0xfffff800, v93
	v_add_u32_e32 v97, 0x800, v93
	v_add_u32_e32 v98, 0xfffff800, v94
	global_load_ushort v84, v80, s[72:73]
	global_load_ushort v83, v77, s[72:73]
	global_load_ushort v82, v79, s[72:73]
	global_load_ushort v81, v78, s[72:73]
	s_nop 0
	global_load_ushort v80, v95, s[72:73]
	global_load_ushort v79, v96, s[72:73]
	global_load_ushort v78, v93, s[72:73]
	global_load_ushort v77, v94, s[72:73]
	v_add_u32_e32 v93, 0x800, v94
	v_mul_lo_u32 v94, v139, s67
	v_cmp_lt_i32_e32 vcc, 0, v139
	v_add_lshl_u32 v94, v94, v6, 1
	s_waitcnt vmcnt(40)
	v_add_u32_e32 v117, 0x800, v94
	v_cndmask_b32_e32 v95, 0, v26, vcc
	v_cmp_gt_i32_e32 vcc, s77, v139
	s_waitcnt vmcnt(38)
	v_add_u32_e32 v115, v94, v95
	v_add_u32_e32 v118, 0xfffff800, v115
	v_cndmask_b32_e32 v95, 0, v27, vcc
	v_add_u32_e32 v116, v94, v95
	v_add_u32_e32 v95, 0xfffff800, v94
	v_add_u32_e32 v119, 0x800, v115
	v_add_u32_e32 v120, 0xfffff800, v116
	global_load_ushort v100, v97, s[72:73]
	global_load_ushort v99, v98, s[72:73]
	s_nop 0
	global_load_ushort v98, v93, s[72:73]
	global_load_ushort v97, v95, s[72:73]
	global_load_ushort v96, v94, s[72:73]
	s_nop 0
	global_load_ushort v95, v117, s[72:73]
	global_load_ushort v94, v115, s[72:73]
	global_load_ushort v93, v116, s[72:73]
	v_add_u32_e32 v115, 0x800, v116
	v_mul_lo_u32 v116, v138, s67
	v_cmp_lt_i32_e32 vcc, 0, v138
	v_add_lshl_u32 v116, v116, v6, 1
	s_waitcnt vmcnt(40)
	v_add_u32_e32 v125, 0x800, v116
	v_cndmask_b32_e32 v117, 0, v26, vcc
	v_cmp_gt_i32_e32 vcc, s77, v138
	s_waitcnt vmcnt(38)
	v_add_u32_e32 v123, v116, v117
	v_add_u32_e32 v126, 0xfffff800, v123
	v_cndmask_b32_e32 v117, 0, v27, vcc
	v_add_u32_e32 v124, v116, v117
	v_add_u32_e32 v117, 0xfffff800, v116
	v_add_u32_e32 v127, 0x800, v123
	s_waitcnt vmcnt(32)
	v_add_u32_e32 v129, 0xfffff800, v124
	global_load_ushort v122, v118, s[72:73]
	global_load_ushort v121, v119, s[72:73]
	s_nop 0
	global_load_ushort v120, v120, s[72:73]
	s_nop 0
	global_load_ushort v119, v115, s[72:73]
	global_load_ushort v118, v117, s[72:73]
	s_nop 0
	global_load_ushort v117, v116, s[72:73]
	s_nop 0
	global_load_ushort v116, v123, s[72:73]
	global_load_ushort v115, v124, s[72:73]
	v_add_u32_e32 v123, 0x800, v124
	v_mul_lo_u32 v124, v137, s67
	v_cmp_lt_i32_e32 vcc, 0, v137
	v_add_lshl_u32 v124, v124, v6, 1
	v_add_u32_e32 v134, 0xfffff800, v124
	v_cndmask_b32_e32 v128, 0, v26, vcc
	v_cmp_gt_i32_e32 vcc, s77, v137
	v_add_u32_e32 v132, v124, v128
	v_add_u32_e32 v135, 0x800, v124
	v_cndmask_b32_e32 v128, 0, v27, vcc
	v_add_u32_e32 v133, v124, v128
	global_load_ushort v131, v125, s[72:73]
	global_load_ushort v130, v126, s[72:73]
	global_load_ushort v128, v127, s[72:73]
	s_nop 0
	global_load_ushort v127, v129, s[72:73]
	global_load_ushort v126, v123, s[72:73]
	global_load_ushort v125, v124, s[72:73]
	s_nop 0
	global_load_ushort v124, v132, s[72:73]
	global_load_ushort v123, v133, s[72:73]
	v_add_u32_e32 v129, 0x800, v133
	v_add_u32_e32 v145, 0xfffff800, v132
	v_add_u32_e32 v147, 0x800, v132
	v_add_u32_e32 v148, 0xfffff800, v133
	global_load_ushort v136, v134, s[72:73]
	s_nop 0
	global_load_ushort v135, v135, s[72:73]
	s_nop 0
	global_load_ushort v134, v145, s[72:73]
	global_load_ushort v133, v147, s[72:73]
	global_load_ushort v132, v148, s[72:73]
	s_nop 0
	global_load_ushort v129, v129, s[72:73]
	s_waitcnt vmcnt(54)
.LBB0_1235:
	s_add_i32 s56, s66, -3
	s_cmp_lt_i32 s56, 0
	s_cbranch_scc1 .LBB0_1255
	v_cndmask_b32_e64 v145, v141, v142, s[0:1]
	v_cmp_lt_i32_e32 vcc, 0, v145
	v_lshlrev_b32_e32 v151, 16, v30
	v_lshlrev_b32_e32 v150, 16, v33
	v_cndmask_b32_e64 v148, 0, 1.0, vcc
	v_cmp_gt_i32_e32 vcc, s77, v145
	v_lshlrev_b32_e32 v147, 16, v36
	v_lshlrev_b32_e32 v152, 16, v29
	v_cndmask_b32_e64 v149, 0, 1.0, vcc
	v_mul_f32_e32 v151, v149, v151
	v_fmac_f32_e32 v151, v148, v150
	v_fma_f32 v150, v151, 0.5, -v147
	v_lshlrev_b32_e32 v151, 16, v32
	v_mul_f32_e32 v152, v149, v152
	v_fmac_f32_e32 v147, v3, v150
	v_lshlrev_b32_e32 v150, 16, v35
	v_fmac_f32_e32 v152, v148, v151
	v_lshlrev_b32_e32 v153, 16, v44
	v_fma_f32 v151, v152, 0.5, -v150
	v_lshlrev_b32_e32 v152, 16, v31
	v_mul_f32_e32 v149, v149, v153
	v_fmac_f32_e32 v150, v4, v151
	v_lshlrev_b32_e32 v151, 16, v34
	v_fmac_f32_e32 v149, v148, v152
	v_fma_f32 v148, v149, 0.5, -v151
	v_mul_f32_e32 v152, v0, v150
	v_fmac_f32_e32 v151, v5, v148
	v_mul_f32_e32 v148, v152, v152
	v_mov_b32_e32 v153, 0
	ds_read_b32 v149, v9 offset:12288
	v_mov_b32_dpp v148, v148 quad_perm:[1,0,3,2] row_mask:0xf bank_mask:0xf bound_ctrl:1
	v_fmac_f32_e32 v148, v152, v152
	s_nop 1
	v_add_f32_dpp v148, v148, v148 quad_perm:[2,3,0,1] row_mask:0xf bank_mask:0xf bound_ctrl:1
	s_nop 1
	v_add_f32_dpp v148, v148, v148 row_half_mirror row_mask:0xf bank_mask:0xf bound_ctrl:1
	s_nop 1
	v_add_f32_dpp v148, v148, v148 row_mirror row_mask:0xf bank_mask:0xf bound_ctrl:1
	s_nop 1
	v_mov_b32_dpp v153, v148 row_bcast:15 row_mask:0xa bank_mask:0xf
	v_add_f32_e32 v148, v148, v153
	v_mov_b32_e32 v153, 0
	s_nop 1
	v_mov_b32_dpp v153, v148 row_bcast:31 row_mask:0xc bank_mask:0xf
	v_add_f32_e32 v148, v148, v153
	s_nop 0
	v_readlane_b32 s56, v148, 63
	s_nop 1
	v_max_f32_e64 v148, s56, s56
	v_max_f32_e32 v148, 0x179abe15, v148
	v_rsq_f32_e32 v153, v148
	s_waitcnt lgkmcnt(0)
	v_add_f32_e32 v148, -1.0, v149
	v_fma_f32 v148, v1, v148, 1.0
	v_mul_f32_e32 v148, v150, v148
	v_mul_f32_e32 v150, v152, v153
	v_add_u32_e32 v152, v7, v8
	v_mul_f32_e32 v149, v149, v150
	ds_write2st64_b32 v152, v150, v149 offset0:80 offset1:81
	ds_write2st64_b32 v152, v148, v147 offset0:82 offset1:83
	ds_write_b32 v152, v151 offset:21504
	s_and_saveexec_b64 s[56:57], s[6:7]
	s_cbranch_execz .LBB0_1239
	v_mul_f32_e32 v147, v147, v148
	v_mul_f32_e32 v148, v2, v147
	s_nop 1
	v_mov_b32_dpp v148, v148 quad_perm:[1,0,3,2] row_mask:0xf bank_mask:0xf bound_ctrl:1
	v_fmac_f32_e32 v148, v2, v147
	s_nop 1
	v_add_f32_dpp v147, v148, v148 quad_perm:[2,3,0,1] row_mask:0xf bank_mask:0xf bound_ctrl:1
	v_mov_b32_e32 v148, 0
	s_nop 0
	v_add_f32_dpp v147, v147, v147 row_half_mirror row_mask:0xf bank_mask:0xf bound_ctrl:1
	s_nop 1
	v_add_f32_dpp v147, v147, v147 row_mirror row_mask:0xf bank_mask:0xf bound_ctrl:1
	s_nop 1
	v_mov_b32_dpp v148, v147 row_bcast:15 row_mask:0xa bank_mask:0xf
	v_add_f32_e32 v147, v147, v148
	v_mov_b32_e32 v148, 0
	s_nop 1
	v_mov_b32_dpp v148, v147 row_bcast:31 row_mask:0xc bank_mask:0xf
	v_add_f32_e32 v147, v147, v148
	s_nop 0
	v_readlane_b32 s81, v147, 63
	s_and_b64 exec, exec, s[4:5]
	s_cbranch_execz .LBB0_1239
	v_lshl_add_u32 v145, v145, 7, s60
	v_mov_b32_e32 v147, s81
	global_store_dword v145, v147, s[24:25]

.LBB0_1255:
	s_waitcnt lgkmcnt(0)
	s_barrier
	s_cmpk_gt_u32 s66, 0x3ff
	v_add_u32_e32 v145, 32, v142
	v_subrev_u32_e32 v147, 32, v141
	s_cbranch_scc1 .Lmy_w6_t2
	s_waitcnt vmcnt(46)
	v_add_u32_e32 v29, 32, v142
	v_subrev_u32_e32 v30, 32, v141
	v_cndmask_b32_e64 v29, v30, v29, s[0:1]
	v_cmp_lt_i32_e32 vcc, 0, v29
	v_mul_lo_u32 v30, v29, s67
	v_add_lshl_u32 v30, v30, v6, 1
	v_cndmask_b32_e32 v31, 0, v26, vcc
	v_cmp_gt_i32_e32 vcc, s77, v29
	v_add_u32_e32 v31, v30, v31
	v_add_u32_e32 v32, 0x800, v30
	v_cndmask_b32_e32 v29, 0, v27, vcc
	s_waitcnt vmcnt(38)
	v_add_u32_e32 v37, v30, v29
	v_add_u32_e32 v29, 0xfffff800, v30
	v_add_u32_e32 v33, 0xfffff800, v31
	v_add_u32_e32 v38, 0x800, v31
	v_add_u32_e32 v39, 0xfffff800, v37
	global_load_ushort v36, v29, s[72:73]
	global_load_ushort v35, v30, s[72:73]
	global_load_ushort v34, v32, s[72:73]
	s_nop 0
	global_load_ushort v33, v33, s[72:73]
	s_nop 0
	global_load_ushort v32, v31, s[72:73]
	s_nop 0
	global_load_ushort v31, v38, s[72:73]
	global_load_ushort v30, v39, s[72:73]
	global_load_ushort v29, v37, s[72:73]
	v_add_u32_e32 v38, 33, v142
	v_subrev_u32_e32 v39, 33, v141
	v_cndmask_b32_e64 v38, v39, v38, s[0:1]
	v_mul_lo_u32 v39, v38, s67
	v_cmp_lt_i32_e32 vcc, 0, v38
	v_add_lshl_u32 v39, v39, v6, 1
	v_add_u32_e32 v37, 0x800, v37
	v_cndmask_b32_e32 v40, 0, v26, vcc
	v_cmp_gt_i32_e32 vcc, s77, v38
	s_waitcnt vmcnt(38)
	v_add_u32_e32 v45, v39, v40
	v_add_u32_e32 v40, 0x800, v39
	v_cndmask_b32_e32 v38, 0, v27, vcc
	v_add_u32_e32 v46, v39, v38
	v_add_u32_e32 v38, 0xfffff800, v39
	v_add_u32_e32 v47, 0xfffff800, v45
	v_add_u32_e32 v48, 0x800, v45
	v_add_u32_e32 v49, 0xfffff800, v46
	global_load_ushort v44, v37, s[72:73]
	global_load_ushort v43, v38, s[72:73]
	global_load_ushort v42, v39, s[72:73]
	global_load_ushort v41, v40, s[72:73]
	s_nop 0
	global_load_ushort v40, v47, s[72:73]
	global_load_ushort v39, v45, s[72:73]
	global_load_ushort v38, v48, s[72:73]
	global_load_ushort v37, v46, s[72:73]
	v_add_u32_e32 v45, 0x800, v46
	v_add_u32_e32 v46, 34, v142
	v_subrev_u32_e32 v47, 34, v141
	v_cndmask_b32_e64 v46, v47, v46, s[0:1]
	v_mul_lo_u32 v47, v46, s67
	v_cmp_lt_i32_e32 vcc, 0, v46
	v_add_lshl_u32 v47, v47, v6, 1
	s_waitcnt vmcnt(27)
	v_subrev_u32_e32 v106, 37, v141
	v_cndmask_b32_e32 v48, 0, v26, vcc
	v_cmp_gt_i32_e32 vcc, s77, v46
	v_add_u32_e32 v69, v47, v48
	v_add_u32_e32 v48, 0x800, v47
	v_cndmask_b32_e32 v46, 0, v27, vcc
	v_add_u32_e32 v70, v47, v46
	v_add_u32_e32 v46, 0xfffff800, v47
	v_add_u32_e32 v71, 0xfffff800, v69
	v_add_u32_e32 v72, 0x800, v69
	v_add_u32_e32 v73, 0xfffff800, v70
	global_load_ushort v52, v49, s[72:73]
	global_load_ushort v51, v45, s[72:73]
	global_load_ushort v50, v46, s[72:73]
	s_nop 0
	global_load_ushort v49, v47, s[72:73]
	s_nop 0
	global_load_ushort v48, v48, s[72:73]
	s_nop 0
	global_load_ushort v47, v71, s[72:73]
	global_load_ushort v46, v69, s[72:73]
	global_load_ushort v45, v70, s[72:73]
	v_add_u32_e32 v69, 0x800, v70
	v_add_u32_e32 v70, 35, v142
	v_subrev_u32_e32 v71, 35, v141
	v_cndmask_b32_e64 v70, v71, v70, s[0:1]
	v_cmp_lt_i32_e32 vcc, 0, v70
	v_mul_lo_u32 v71, v70, s67
	v_add_lshl_u32 v71, v71, v6, 1
	v_cndmask_b32_e32 v74, 0, v26, vcc
	v_cmp_gt_i32_e32 vcc, s77, v70
	v_add_u32_e32 v85, v71, v74
	v_add_u32_e32 v87, 0x800, v71
	v_cndmask_b32_e32 v70, 0, v27, vcc
	v_add_u32_e32 v86, v71, v70
	v_add_u32_e32 v70, 0xfffff800, v71
	v_add_u32_e32 v88, 0xfffff800, v85
	v_add_u32_e32 v89, 0x800, v85
	v_add_u32_e32 v90, 0xfffff800, v86
	global_load_ushort v76, v72, s[72:73]
	global_load_ushort v75, v73, s[72:73]
	global_load_ushort v74, v69, s[72:73]
	s_nop 0
	global_load_ushort v73, v70, s[72:73]
	global_load_ushort v72, v71, s[72:73]
	s_nop 0
	global_load_ushort v71, v87, s[72:73]
	global_load_ushort v70, v85, s[72:73]
	global_load_ushort v69, v86, s[72:73]
	v_add_u32_e32 v85, 0x800, v86
	v_add_u32_e32 v86, 36, v142
	v_subrev_u32_e32 v87, 36, v141
	v_cndmask_b32_e64 v86, v87, v86, s[0:1]
	v_cmp_lt_i32_e32 vcc, 0, v86
	v_mul_lo_u32 v87, v86, s67
	v_add_lshl_u32 v87, v87, v6, 1
	v_cndmask_b32_e32 v91, 0, v26, vcc
	v_cmp_gt_i32_e32 vcc, s77, v86
	s_waitcnt vmcnt(38)
	v_add_u32_e32 v101, v87, v91
	v_add_u32_e32 v103, 0x800, v87
	v_cndmask_b32_e32 v86, 0, v27, vcc
	v_add_u32_e32 v102, v87, v86
	v_add_u32_e32 v86, 0xfffff800, v87
	v_add_u32_e32 v104, 0xfffff800, v101
	v_add_u32_e32 v105, 0x800, v101
	s_waitcnt vmcnt(32)
	v_add_u32_e32 v107, 0xfffff800, v102
	global_load_ushort v92, v88, s[72:73]
	global_load_ushort v91, v89, s[72:73]
	s_nop 0
	global_load_ushort v90, v90, s[72:73]
	s_nop 0
	global_load_ushort v89, v85, s[72:73]
	global_load_ushort v88, v86, s[72:73]
	s_nop 0
	global_load_ushort v87, v87, s[72:73]
	s_nop 0
	global_load_ushort v86, v101, s[72:73]
	global_load_ushort v85, v102, s[72:73]
	v_add_u32_e32 v101, 0x800, v102
	v_add_u32_e32 v102, 37, v142
	v_cndmask_b32_e64 v102, v106, v102, s[0:1]
	v_mul_lo_u32 v106, v102, s67
	v_cmp_lt_i32_e32 vcc, 0, v102
	v_add_lshl_u32 v110, v106, v6, 1
	v_add_u32_e32 v113, 0xfffff800, v110
	v_cndmask_b32_e32 v106, 0, v26, vcc
	v_cmp_gt_i32_e32 vcc, s77, v102
	v_add_u32_e32 v111, v110, v106
	v_add_u32_e32 v141, 0x800, v110
	v_cndmask_b32_e32 v102, 0, v27, vcc
	v_add_u32_e32 v112, v110, v102
	global_load_ushort v109, v103, s[72:73]
	global_load_ushort v108, v104, s[72:73]
	global_load_ushort v106, v105, s[72:73]
	s_nop 0
	global_load_ushort v105, v107, s[72:73]
	global_load_ushort v104, v101, s[72:73]
	global_load_ushort v103, v110, s[72:73]
	global_load_ushort v102, v111, s[72:73]
	s_nop 0
	global_load_ushort v101, v112, s[72:73]
	v_add_u32_e32 v107, 0x800, v112
	v_add_u32_e32 v142, 0xfffff800, v111
	v_add_u32_e32 v148, 0x800, v111
	v_add_u32_e32 v149, 0xfffff800, v112
	global_load_ushort v114, v113, s[72:73]
	s_nop 0
	global_load_ushort v113, v141, s[72:73]
	global_load_ushort v112, v142, s[72:73]
	global_load_ushort v111, v148, s[72:73]
	global_load_ushort v110, v149, s[72:73]
	s_nop 0
	global_load_ushort v107, v107, s[72:73]
	s_waitcnt vmcnt(54)
.LBB0_1257:
	s_andn2_b64 vcc, exec, s[54:55]
	s_cbranch_vccnz .LBB0_1232
	v_cmp_lt_i32_e32 vcc, 0, v144
	v_lshlrev_b32_e32 v149, 16, v57
	v_lshlrev_b32_e32 v150, 16, v54
	v_cndmask_b32_e64 v142, 0, 1.0, vcc
	v_cmp_gt_i32_e32 vcc, s77, v144
	v_mul_f32_e32 v149, v142, v149
	v_lshlrev_b32_e32 v141, 16, v60
	v_cndmask_b32_e64 v148, 0, 1.0, vcc
	v_fmac_f32_e32 v149, v148, v150
	v_lshlrev_b32_e32 v150, 16, v56
	v_fma_f32 v149, v149, 0.5, -v141
	v_mul_f32_e32 v150, v142, v150
	v_lshlrev_b32_e32 v151, 16, v53
	v_fmac_f32_e32 v141, v3, v149
	v_lshlrev_b32_e32 v149, 16, v59
	v_fmac_f32_e32 v150, v148, v151
	v_lshlrev_b32_e32 v151, 16, v55
	v_fma_f32 v150, v150, 0.5, -v149
	v_mul_f32_e32 v142, v142, v151
	v_lshlrev_b32_e32 v151, 16, v68
	v_fmac_f32_e32 v149, v4, v150
	v_lshlrev_b32_e32 v150, 16, v58
	v_fmac_f32_e32 v142, v148, v151
	v_fma_f32 v142, v142, 0.5, -v150
	v_mul_f32_e32 v151, v0, v149
	v_fmac_f32_e32 v150, v5, v142
	v_mul_f32_e32 v142, v151, v151
	v_mov_b32_e32 v152, 0
	ds_read_b32 v148, v20 offset:12288
	v_mov_b32_dpp v142, v142 quad_perm:[1,0,3,2] row_mask:0xf bank_mask:0xf bound_ctrl:1
	v_fmac_f32_e32 v142, v151, v151
	s_nop 1
	v_add_f32_dpp v142, v142, v142 quad_perm:[2,3,0,1] row_mask:0xf bank_mask:0xf bound_ctrl:1
	s_nop 1
	v_add_f32_dpp v142, v142, v142 row_half_mirror row_mask:0xf bank_mask:0xf bound_ctrl:1
	s_nop 1
	v_add_f32_dpp v142, v142, v142 row_mirror row_mask:0xf bank_mask:0xf bound_ctrl:1
	s_nop 1
	v_mov_b32_dpp v152, v142 row_bcast:15 row_mask:0xa bank_mask:0xf
	v_add_f32_e32 v142, v142, v152
	v_mov_b32_e32 v152, 0
	s_nop 1
	v_mov_b32_dpp v152, v142 row_bcast:31 row_mask:0xc bank_mask:0xf
	v_add_f32_e32 v142, v142, v152
	s_nop 0
	v_readlane_b32 s54, v142, 63
	s_nop 1
	v_max_f32_e64 v142, s54, s54
	v_max_f32_e32 v142, 0x179abe15, v142
	v_rsq_f32_e32 v152, v142
	s_waitcnt lgkmcnt(0)
	v_add_f32_e32 v142, -1.0, v148
	v_fma_f32 v142, v1, v142, 1.0
	v_mul_f32_e32 v142, v149, v142
	v_mul_f32_e32 v149, v151, v152
	v_mul_f32_e32 v148, v148, v149
	ds_write2st64_b32 v28, v149, v148 offset0:80 offset1:81
	ds_write2st64_b32 v28, v142, v141 offset0:82 offset1:83
	ds_write_b32 v28, v150 offset:21504
	s_and_saveexec_b64 s[54:55], s[6:7]
	s_cbranch_execz .LBB0_1261
	v_mul_f32_e32 v141, v141, v142
	v_mul_f32_e32 v142, v2, v141
	s_nop 1
	v_mov_b32_dpp v142, v142 quad_perm:[1,0,3,2] row_mask:0xf bank_mask:0xf bound_ctrl:1
	v_fmac_f32_e32 v142, v2, v141
	s_nop 1
	v_add_f32_dpp v141, v142, v142 quad_perm:[2,3,0,1] row_mask:0xf bank_mask:0xf bound_ctrl:1
	v_mov_b32_e32 v142, 0
	s_nop 0
	v_add_f32_dpp v141, v141, v141 row_half_mirror row_mask:0xf bank_mask:0xf bound_ctrl:1
	s_nop 1
	v_add_f32_dpp v141, v141, v141 row_mirror row_mask:0xf bank_mask:0xf bound_ctrl:1
	s_nop 1
	v_mov_b32_dpp v142, v141 row_bcast:15 row_mask:0xa bank_mask:0xf
	v_add_f32_e32 v141, v141, v142
	v_mov_b32_e32 v142, 0
	s_nop 1
	v_mov_b32_dpp v142, v141 row_bcast:31 row_mask:0xc bank_mask:0xf
	v_add_f32_e32 v141, v141, v142
	s_nop 0
	v_readlane_b32 s56, v141, 63
	s_and_b64 exec, exec, s[4:5]
	s_cbranch_execz .LBB0_1261
	v_lshl_add_u32 v141, v144, 7, s60
	v_mov_b32_e32 v142, s56
	global_store_dword v141, v142, s[24:25]

; template <int NS, bool LORA, int mat> ...
;     ...
;   bf16x8 bw[4][2]; float bias[4]; float mu0[8], mu1[8];
;   const int colA = 3072 + mat * 128 + dir * 64 + fq * 8;
;   if (LORA) {
;     const u16* WT = (const u16*)(p.ws + (mat ? OFF_A2T : OFF_W2T)) + ((size_t)dir * 1024 + 64 * head + fr) * 64 + fq * 8;
; #pragma unroll
;     for (int nt = 0; nt < 4; ++nt) {
;       bw[nt][0] = *(const bf16x8*)(WT + nt * 16 * 64);
;       bw[nt][1] = *(const bf16x8*)(WT + nt * 16 * 64 + 32);
;       bias[nt] = (mat ? p.a0 : p.w0)[dir * 1024 + 64 * head + nt * 16 + fr];
;     }
; #pragma unroll
;     for (int j = 0; j < 8; ++j) { mu0[j] = p.mu_shift[colA + j]; mu1[j] = p.mu_shift[colA + 32 + j]; }
;   }
;   const int ch = 64 * head + lane;
;   const float kk_c = p.k_k[ch], ka_c = p.k_a[ch], rk_c = p.r_k[ch];
;   const float mu_r = p.mu_shift[ch], mu_k = p.mu_shift[1024 + ch], mu_v = p.mu_shift[2048 + ch];
;   uint4 la[2][6];
;   u16 rv[2][NS][9];
.LBB0_1276:
	s_andn2_saveexec_b64 s[12:13], s[52:53]
	s_cbranch_execz .LBB0_1318
	s_waitcnt vmcnt(5)
	v_and_b32_e32 v114, 15, v140
	v_or_b32_e32 v0, s64, v114
	s_waitcnt vmcnt(4)
	v_mov_b32_e32 v1, s65
	v_lshrrev_b32_e32 v74, 4, v148
	v_lshlrev_b64 v[0:1], 7, v[0:1]
	v_lshl_or_b32 v40, v74, 3, s63
	v_lshl_add_u64 v[0:1], s[42:43], 0, v[0:1]
	v_and_b32_e32 v88, 48, v148
	v_mov_b32_e32 v89, 0
	v_lshl_add_u64 v[16:17], v[0:1], 0, v[88:89]
	s_movk_i32 s4, 0x1000
	v_lshlrev_b32_e32 v88, 2, v40
	v_add_co_u32_e32 v28, vcc, s4, v16
	v_or_b32_e32 v119, 0xc80, v40
	v_lshl_add_u64 v[40:41], s[38:39], 0, v[88:89]
	s_mov_b64 s[4:5], 0x3280
	v_or_b32_e32 v72, s61, v148
	v_or_b32_e32 v8, s62, v114
	v_addc_co_u32_e32 v29, vcc, 0, v17, vcc
	v_lshl_add_u64 v[44:45], v[40:41], 0, s[4:5]
	s_movk_i32 s4, 0x3000
	v_ashrrev_i32_e32 v73, 31, v72
	v_ashrrev_i32_e32 v9, 31, v8
	v_add_co_u32_e32 v40, vcc, s4, v40
	v_lshlrev_b64 v[48:49], 2, v[72:73]
	v_lshl_add_u64 v[32:33], v[8:9], 2, s[44:45]
	v_lshlrev_b32_e32 v36, 2, v119
	v_addc_co_u32_e32 v41, vcc, 0, v41, vcc
	v_lshl_add_u64 v[50:51], s[50:51], 0, v[48:49]
	global_load_dwordx4 v[0:3], v[16:17], off
	global_load_dwordx4 v[4:7], v[16:17], off offset:64
	global_load_dwordx4 v[8:11], v[16:17], off offset:2048
	global_load_dwordx4 v[12:15], v[16:17], off offset:2112
	s_nop 0
	global_load_dwordx4 v[16:19], v[28:29], off
	global_load_dwordx4 v[20:23], v[28:29], off offset:64
	global_load_dwordx4 v[24:27], v[28:29], off offset:2048
	s_nop 0
	global_load_dwordx4 v[28:31], v[28:29], off offset:2112
	s_nop 0
	global_load_dword v115, v[32:33], off
	global_load_dword v116, v[32:33], off offset:64
	global_load_dword v117, v[32:33], off offset:128
	global_load_dword v118, v[32:33], off offset:192
	s_nop 0
	global_load_dwordx4 v[32:35], v36, s[38:39]
	s_nop 0
	global_load_dwordx4 v[36:39], v36, s[38:39] offset:16
	s_nop 0
	global_load_dwordx4 v[40:43], v[40:41], off offset:640
	s_nop 0
	global_load_dwordx4 v[44:47], v[44:45], off offset:16
	s_movk_i32 s4, 0x2000
	global_load_dword v120, v[50:51], off
	v_lshl_add_u64 v[50:51], s[16:17], 0, v[48:49]
	global_load_dword v121, v[50:51], off
	v_lshl_add_u64 v[50:51], s[18:19], 0, v[48:49]
	v_lshl_add_u64 v[48:49], s[38:39], 0, v[48:49]
	global_load_dword v123, v[48:49], off
	v_add_co_u32_e32 v48, vcc, s4, v48
	s_movk_i32 s54, 0x3fff
	s_nop 0
	v_addc_co_u32_e32 v49, vcc, 0, v49, vcc
	global_load_dword v122, v[50:51], off
	global_load_dword v124, v[48:49], off offset:-4096
	global_load_dword v125, v[48:49], off
	v_bitop3_b32 v48, v140, s54, 15 bitop3:0x6c
	v_cndmask_b32_e64 v50, v48, v114, s[0:1]
	v_mul_u32_u24_e32 v48, 0xe00, v50
	v_mov_b32_e32 v126, 0xffffe400
	v_cmp_eq_u32_e32 vcc, 0, v50
	v_add_lshl_u32 v88, v119, v48, 1
	v_mov_b32_e32 v127, 0x1c00
	v_cndmask_b32_e64 v48, v126, 0, vcc
	v_cmp_eq_u32_e32 vcc, s54, v50
	v_add_u32_e32 v64, v88, v48
	v_lshl_add_u64 v[48:49], s[72:73], 0, v[88:89]
	v_cndmask_b32_e64 v50, v127, 0, vcc
	v_mov_b32_e32 v51, v89
	v_lshl_add_u64 v[68:69], v[48:49], 0, v[50:51]
	global_load_dwordx4 v[48:51], v64, s[72:73]
	global_load_dwordx4 v[52:55], v[68:69], off
	global_load_dwordx4 v[56:59], v88, s[72:73]
	global_load_dwordx4 v[60:63], v88, s[72:73] offset:64
	v_add_u32_e32 v64, 64, v64
	global_load_dwordx4 v[64:67], v64, s[72:73]
	s_nop 0
	global_load_dwordx4 v[68:71], v[68:69], off offset:64
	s_cmp_eq_u32 s3, 1
	s_cselect_b64 s[14:15], -1, 0
	s_cmp_eq_u32 s3, 2
	s_cselect_b64 s[42:43], -1, 0
	s_cmp_eq_u32 s3, 3
	v_lshl_add_u32 v73, v114, 2, 0
	v_add_u32_e32 v128, 0x400, v72
	v_lshlrev_b32_e32 v72, 10, v74
	s_mov_b32 s55, 2
	s_cselect_b64 s[44:45], -1, 0
	s_movk_i32 s56, 0xe00
	s_waitcnt vmcnt(28)
	v_lshl_add_u32 v129, v148, 2, 0
	v_cmp_eq_u32_e64 s[4:5], 0, v148
	v_sub_u32_e32 v130, 0, v114
	s_mov_b32 s57, -15
	s_movk_i32 s66, 0x400e
	v_add_u32_e32 v131, v73, v72
	v_mov_b32_e32 v132, 0
	v_mov_b32_e32 v133, 0
	v_mov_b32_e32 v134, 0
	v_mov_b32_e32 v135, 0
	v_mov_b32_e32 v136, 0
	v_mov_b32_e32 v137, 0
	v_mov_b32_e32 v138, 0
	v_mov_b32_e32 v139, 0
	v_mov_b32_e32 v145, 0
	v_mov_b32_e32 v148, 0
	v_mov_b32_e32 v150, 0
	v_mov_b32_e32 v152, 0
	v_mov_b32_e32 v153, 0
	v_mov_b32_e32 v154, 0
	v_mov_b32_e32 v155, 0
	v_mov_b32_e32 v162, 0
	v_mov_b32_e32 v156, 0
	v_mov_b32_e32 v165, 0
	v_mov_b32_e32 v166, 0
	v_mov_b32_e32 v168, 0
	v_mov_b32_e32 v169, 0
	v_mov_b32_e32 v170, 0
	v_mov_b32_e32 v171, 0
	v_mov_b32_e32 v172, 0
	v_mov_b32_e32 v174, 0
	v_mov_b32_e32 v173, 0
	v_mov_b32_e32 v175, 0
	v_mov_b32_e32 v140, 0
	v_mov_b32_e32 v141, 0
	v_mov_b32_e32 v142, 0
	v_mov_b32_e32 v143, 0
	v_mov_b32_e32 v144, 0
	v_mov_b32_e32 v147, 0
	v_mov_b32_e32 v149, 0
	v_mov_b32_e32 v151, 0
	v_mov_b32_e32 v157, 0
	v_mov_b32_e32 v158, 0
	v_mov_b32_e32 v159, 0
	v_mov_b32_e32 v160, 0
	v_mov_b32_e32 v161, 0
	v_mov_b32_e32 v163, 0
	v_mov_b32_e32 v164, 0
	v_mov_b32_e32 v176, 0
	v_mov_b32_e32 v167, 0
	v_mov_b32_e32 v177, 0
	v_mov_b32_e32 v178, 0
	v_mov_b32_e32 v179, 0
	v_mov_b32_e32 v180, 0
	v_mov_b32_e32 v181, 0
	v_mov_b32_e32 v182, 0
	v_mov_b32_e32 v183, 0
	v_mov_b32_e32 v185, 0
	v_mov_b32_e32 v184, 0
	v_mov_b32_e32 v186, 0
	s_waitcnt vmcnt(0)
	s_branch .LBB0_1280

.LBB0_1280:
	s_add_i32 s6, s55, -1
	s_cmpk_lt_u32 s6, 0x400
	v_add_u32_e32 v189, s66, v130
	s_cselect_b64 s[52:53], -1, 0
	s_cmpk_gt_u32 s6, 0x3ff
	v_add3_u32 v187, v114, s57, 31
	v_subrev_u32_e32 v188, 31, v189
	s_cbranch_scc1 .LBB0_1282
	v_cndmask_b32_e64 v74, v188, v187, s[0:1]
	v_mul_lo_u32 v72, v74, s56
	v_cmp_eq_u32_e32 vcc, 0, v74
	v_add_lshl_u32 v88, v72, v119, 1
	v_mov_b32_e32 v75, v89
	v_cndmask_b32_e64 v72, v126, 0, vcc
	v_add_u32_e32 v76, v88, v72
	v_cmp_gt_u32_e32 vcc, s54, v74
	v_lshl_add_u64 v[72:73], s[72:73], 0, v[88:89]
	global_load_dwordx4 v[226:229], v76, s[72:73]
	v_cndmask_b32_e32 v74, 0, v127, vcc
	v_lshl_add_u64 v[72:73], v[72:73], 0, v[74:75]
	v_add_u32_e32 v74, 64, v76
	global_load_dwordx4 v[230:233], v[72:73], off offset:64
	global_load_dwordx4 v[234:237], v74, s[72:73]
	global_load_dwordx4 v[238:241], v[72:73], off
	s_nop 0
	global_load_dwordx4 v[72:75], v88, s[72:73]
	global_load_dwordx4 v[76:79], v88, s[72:73] offset:64
	s_branch .LBB0_1283

.LBB0_1283:
	s_add_i32 s67, s55, -2
	s_cmpk_lt_u32 s67, 0x400
	s_cselect_b64 s[8:9], -1, 0
	s_cmpk_gt_u32 s67, 0x3ff
	s_cbranch_scc1 .LBB0_1285
	s_add_i32 s10, s57, 16
	s_add_i32 s11, s66, -16
	s_and_b64 s[6:7], s[0:1], exec
	s_cselect_b32 s6, s10, s11
	s_mulk_i32 s6, 0xe00
	s_add_i32 s10, s57, 17
	s_sub_i32 s11, s66, 17
	v_add_lshl_u32 v88, s6, v128, 1
	s_and_b64 s[6:7], s[0:1], exec
	s_cselect_b32 s6, s10, s11
	s_mulk_i32 s6, 0xe00
	s_add_i32 s10, s57, 18
	s_sub_i32 s11, s66, 18
	v_add_lshl_u32 v162, s6, v128, 1
	s_and_b64 s[6:7], s[0:1], exec
	s_cselect_b32 s6, s10, s11
	s_mulk_i32 s6, 0xe00
	v_add_u32_e32 v136, 0xffffe400, v88
	v_add_u32_e32 v139, 0x1c00, v88
	v_add_u32_e32 v132, 0xfffff800, v88
	v_add_u32_e32 v134, 0x800, v88
	v_add_u32_e32 v135, 0xffffdc00, v88
	v_add_u32_e32 v137, 0xffffec00, v88
	v_add_u32_e32 v138, 0x1400, v88
	v_add_lshl_u32 v172, s6, v128, 1
	global_load_ushort v132, v132, s[72:73]
	s_nop 0
	global_load_ushort v133, v88, s[72:73]
	s_nop 0
	global_load_ushort v134, v134, s[72:73]
	s_nop 0
	global_load_ushort v135, v135, s[72:73]
	s_nop 0
	global_load_ushort v136, v136, s[72:73]
	s_nop 0
	global_load_ushort v137, v137, s[72:73]
	s_nop 0
	global_load_ushort v138, v138, s[72:73]
	s_nop 0
	global_load_ushort v139, v139, s[72:73]
	v_add_u32_e32 v88, 0x2400, v88
	v_add_u32_e32 v154, 0xffffe400, v162
	v_add_u32_e32 v156, 0x1c00, v162
	v_add_u32_e32 v148, 0xfffff800, v162
	v_add_u32_e32 v152, 0x800, v162
	v_add_u32_e32 v153, 0xffffdc00, v162
	v_add_u32_e32 v155, 0xffffec00, v162
	v_add_u32_e32 v165, 0x1400, v162
	v_add_u32_e32 v171, 0xffffe400, v172
	v_add_u32_e32 v173, 0x1c00, v172
	v_add_u32_e32 v166, 0xfffff800, v172
	v_add_u32_e32 v169, 0x800, v172
	v_add_u32_e32 v170, 0xffffdc00, v172
	global_load_ushort v145, v88, s[72:73]
	s_nop 0
	global_load_ushort v148, v148, s[72:73]
	s_nop 0
	global_load_ushort v150, v162, s[72:73]
	s_nop 0
	global_load_ushort v152, v152, s[72:73]
	s_nop 0
	global_load_ushort v153, v153, s[72:73]
	s_nop 0
	global_load_ushort v154, v154, s[72:73]
	s_nop 0
	global_load_ushort v155, v155, s[72:73]
	s_nop 0
	global_load_ushort v156, v156, s[72:73]
	v_add_u32_e32 v88, 0x2400, v162
	global_load_ushort v162, v165, s[72:73]
	s_nop 0
	global_load_ushort v165, v88, s[72:73]
	s_nop 0
	global_load_ushort v166, v166, s[72:73]
	s_nop 0
	global_load_ushort v168, v172, s[72:73]
	s_nop 0
	global_load_ushort v169, v169, s[72:73]
	s_nop 0
	global_load_ushort v170, v170, s[72:73]
	s_nop 0
	global_load_ushort v171, v171, s[72:73]
	s_nop 0
	global_load_ushort v173, v173, s[72:73]
	v_add_u32_e32 v174, 0xffffec00, v172
	v_add_u32_e32 v175, 0x1400, v172
	v_add_u32_e32 v88, 0x2400, v172
	global_load_ushort v172, v174, s[72:73]
	s_nop 0
	global_load_ushort v174, v175, s[72:73]
	s_nop 0
	global_load_ushort v175, v88, s[72:73]
.LBB0_1285:
	v_cndmask_b32_e64 v88, 0, 1, s[8:9]
	v_cmp_ne_u32_e64 s[6:7], 1, v88
	s_andn2_b64 vcc, exec, s[8:9]
	s_cbranch_vccnz .LBB0_1287
	v_add3_u32 v88, v114, s57, 15
	v_add3_u32 v190, v130, s66, -15
	v_cndmask_b32_e64 v88, v190, v88, s[0:1]
	v_cmp_eq_u32_e32 vcc, 0, v88
	v_lshlrev_b32_e32 v196, 16, v48
	v_and_b32_e32 v197, 0xffff0000, v52
	v_cndmask_b32_e64 v195, 1.0, 0, vcc
	v_cmp_gt_u32_e32 vcc, s54, v88
	v_lshlrev_b32_e32 v192, 16, v52
	v_and_b32_e32 v193, 0xffff0000, v48
	v_cndmask_b32_e64 v194, 0, 1.0, vcc
	v_pk_mul_f32 v[196:197], v[194:195], v[196:197] op_sel:[1,0] op_sel_hi:[0,1]
	v_lshlrev_b32_e32 v190, 16, v56
	v_and_b32_e32 v191, 0xffff0000, v56
	v_pk_fma_f32 v[192:193], v[194:195], v[192:193], v[196:197]
	v_lshlrev_b32_e32 v198, 16, v49
	v_and_b32_e32 v199, 0xffff0000, v53
	v_pk_fma_f32 v[192:193], v[192:193], 0.5, v[190:191] op_sel_hi:[1,0,1] neg_lo:[0,0,1] neg_hi:[0,0,1]
	v_lshlrev_b32_e32 v196, 16, v53
	v_and_b32_e32 v197, 0xffff0000, v49
	v_pk_mul_f32 v[198:199], v[194:195], v[198:199] op_sel:[1,0] op_sel_hi:[0,1]
	v_pk_fma_f32 v[190:191], v[32:33], v[192:193], v[190:191]
	v_lshlrev_b32_e32 v192, 16, v57
	v_and_b32_e32 v193, 0xffff0000, v57
	v_pk_fma_f32 v[196:197], v[194:195], v[196:197], v[198:199]
	v_lshlrev_b32_e32 v200, 16, v50
	v_and_b32_e32 v201, 0xffff0000, v54
	v_pk_fma_f32 v[196:197], v[196:197], 0.5, v[192:193] op_sel_hi:[1,0,1] neg_lo:[0,0,1] neg_hi:[0,0,1]
	v_lshlrev_b32_e32 v198, 16, v54
	v_and_b32_e32 v199, 0xffff0000, v50
	v_pk_mul_f32 v[200:201], v[194:195], v[200:201] op_sel:[1,0] op_sel_hi:[0,1]
	v_pk_fma_f32 v[192:193], v[34:35], v[196:197], v[192:193]
	v_lshlrev_b32_e32 v196, 16, v58
	v_and_b32_e32 v197, 0xffff0000, v58
	v_pk_fma_f32 v[198:199], v[194:195], v[198:199], v[200:201]
	v_lshlrev_b32_e32 v202, 16, v51
	v_and_b32_e32 v203, 0xffff0000, v55
	v_pk_fma_f32 v[198:199], v[198:199], 0.5, v[196:197] op_sel_hi:[1,0,1] neg_lo:[0,0,1] neg_hi:[0,0,1]
	v_lshlrev_b32_e32 v200, 16, v55
	v_and_b32_e32 v201, 0xffff0000, v51
	v_pk_mul_f32 v[202:203], v[194:195], v[202:203] op_sel:[1,0] op_sel_hi:[0,1]
	v_pk_fma_f32 v[196:197], v[36:37], v[198:199], v[196:197]
	v_lshlrev_b32_e32 v198, 16, v59
	v_and_b32_e32 v199, 0xffff0000, v59
	v_pk_fma_f32 v[200:201], v[194:195], v[200:201], v[202:203]
	v_cvt_pk_bf16_f32 v190, v190, v191
	v_pk_fma_f32 v[200:201], v[200:201], 0.5, v[198:199] op_sel_hi:[1,0,1] neg_lo:[0,0,1] neg_hi:[0,0,1]
	v_cvt_pk_bf16_f32 v191, v192, v193
	v_pk_fma_f32 v[198:199], v[38:39], v[200:201], v[198:199]
	v_lshlrev_b32_e32 v200, 16, v64
	v_and_b32_e32 v201, 0xffff0000, v68
	v_cvt_pk_bf16_f32 v193, v198, v199
	v_lshlrev_b32_e32 v198, 16, v68
	v_and_b32_e32 v199, 0xffff0000, v64
	v_pk_mul_f32 v[200:201], v[194:195], v[200:201] op_sel:[1,0] op_sel_hi:[0,1]
	v_cvt_pk_bf16_f32 v192, v196, v197
	v_lshlrev_b32_e32 v196, 16, v60
	v_and_b32_e32 v197, 0xffff0000, v60
	v_pk_fma_f32 v[198:199], v[194:195], v[198:199], v[200:201]
	v_lshlrev_b32_e32 v202, 16, v65
	v_and_b32_e32 v203, 0xffff0000, v69
	v_pk_fma_f32 v[198:199], v[198:199], 0.5, v[196:197] op_sel_hi:[1,0,1] neg_lo:[0,0,1] neg_hi:[0,0,1]
	v_lshlrev_b32_e32 v200, 16, v69
	v_and_b32_e32 v201, 0xffff0000, v65
	v_pk_mul_f32 v[202:203], v[194:195], v[202:203] op_sel:[1,0] op_sel_hi:[0,1]
	v_pk_fma_f32 v[196:197], v[40:41], v[198:199], v[196:197]
	v_lshlrev_b32_e32 v198, 16, v61
	v_and_b32_e32 v199, 0xffff0000, v61
	v_pk_fma_f32 v[200:201], v[194:195], v[200:201], v[202:203]
	v_lshlrev_b32_e32 v204, 16, v66
	v_and_b32_e32 v205, 0xffff0000, v70
	v_pk_fma_f32 v[200:201], v[200:201], 0.5, v[198:199] op_sel_hi:[1,0,1] neg_lo:[0,0,1] neg_hi:[0,0,1]
	v_lshlrev_b32_e32 v202, 16, v70
	v_and_b32_e32 v203, 0xffff0000, v66
	v_pk_mul_f32 v[204:205], v[194:195], v[204:205] op_sel:[1,0] op_sel_hi:[0,1]
	v_pk_fma_f32 v[198:199], v[42:43], v[200:201], v[198:199]
	v_lshlrev_b32_e32 v200, 16, v62
	v_and_b32_e32 v201, 0xffff0000, v62
	v_pk_fma_f32 v[202:203], v[194:195], v[202:203], v[204:205]
	v_lshlrev_b32_e32 v206, 16, v67
	v_and_b32_e32 v207, 0xffff0000, v71
	v_pk_fma_f32 v[202:203], v[202:203], 0.5, v[200:201] op_sel_hi:[1,0,1] neg_lo:[0,0,1] neg_hi:[0,0,1]
	v_lshlrev_b32_e32 v204, 16, v71
	v_and_b32_e32 v205, 0xffff0000, v67
	v_pk_mul_f32 v[206:207], v[194:195], v[206:207] op_sel:[1,0] op_sel_hi:[0,1]
	v_pk_fma_f32 v[200:201], v[44:45], v[202:203], v[200:201]
	v_lshlrev_b32_e32 v202, 16, v63
	v_and_b32_e32 v203, 0xffff0000, v63
	v_pk_fma_f32 v[194:195], v[194:195], v[204:205], v[206:207]
	s_nop 0
	v_pk_fma_f32 v[194:195], v[194:195], 0.5, v[202:203] op_sel_hi:[1,0,1] neg_lo:[0,0,1] neg_hi:[0,0,1]
	s_nop 0
	v_pk_fma_f32 v[202:203], v[46:47], v[194:195], v[202:203]
	v_cvt_pk_bf16_f32 v194, v196, v197
	v_cvt_pk_bf16_f32 v195, v198, v199
	v_cvt_pk_bf16_f32 v196, v200, v201
	v_cvt_pk_bf16_f32 v197, v202, v203
	v_mfma_f32_16x16x32_bf16 v[198:201], v[190:193], v[0:3], 0
	s_nop 0
	v_mfma_f32_16x16x32_bf16 v[198:201], v[194:197], v[4:7], v[198:201]
	v_mfma_f32_16x16x32_bf16 v[202:205], v[190:193], v[8:11], 0
	s_nop 6
	v_add_f32_e32 v88, v115, v198
	v_add_f32_e32 v198, v115, v199
	v_mul_f32_e32 v198, 0xbfb8aa3b, v198
	v_exp_f32_e32 v198, v198
	v_add_f32_e32 v199, v115, v200
	v_mul_f32_e32 v199, 0xbfb8aa3b, v199
	v_exp_f32_e32 v199, v199
	v_add_f32_e32 v198, 1.0, v198
	v_rcp_f32_e32 v206, v198
	v_add_f32_e32 v198, v115, v201
	v_mul_f32_e32 v198, 0xbfb8aa3b, v198
	v_add_f32_e32 v207, 1.0, v199
	v_exp_f32_e32 v208, v198
	v_mfma_f32_16x16x32_bf16 v[198:201], v[194:197], v[12:15], v[202:205]
	v_mul_f32_e32 v88, 0xbfb8aa3b, v88
	v_exp_f32_e32 v88, v88
	s_nop 0
	v_add_u32_e32 v204, 0x3000, v131
	v_rcp_f32_e32 v202, v207
	s_nop 2
	v_add_f32_e32 v198, v116, v198
	v_mul_f32_e32 v198, 0xbfb8aa3b, v198
	v_exp_f32_e32 v198, v198
	v_add_f32_e32 v200, v116, v200
	v_add_f32_e32 v88, 1.0, v88
	v_mul_f32_e32 v200, 0xbfb8aa3b, v200
	v_add_f32_e32 v198, 1.0, v198
	v_rcp_f32_e32 v88, v88
	v_rcp_f32_e32 v198, v198
	v_exp_f32_e32 v200, v200
	v_add_f32_e32 v199, v116, v199
	v_mul_f32_e32 v199, 0xbfb8aa3b, v199
	v_exp_f32_e32 v199, v199
	ds_write2_b32 v204, v88, v198 offset1:16
	v_add_f32_e32 v198, 1.0, v200
	v_rcp_f32_e32 v205, v198
	v_add_f32_e32 v198, v116, v201
	v_mul_f32_e32 v198, 0xbfb8aa3b, v198
	v_add_f32_e32 v88, 1.0, v199
	v_exp_f32_e32 v207, v198
	v_mfma_f32_16x16x32_bf16 v[198:201], v[190:193], v[16:19], 0
	v_rcp_f32_e32 v88, v88
	v_add_f32_e32 v203, 1.0, v208
	v_rcp_f32_e32 v203, v203
	v_mfma_f32_16x16x32_bf16 v[198:201], v[194:197], v[20:23], v[198:201]
	ds_write2_b32 v204, v206, v88 offset0:64 offset1:80
	v_add_f32_e32 v88, 1.0, v207
	v_rcp_f32_e32 v88, v88
	v_mfma_f32_16x16x32_bf16 v[190:193], v[190:193], v[24:27], 0
	ds_write2_b32 v204, v202, v205 offset0:128 offset1:144
	s_nop 2
	v_add_f32_e32 v198, v117, v198
	v_add_f32_e32 v199, v117, v199
	v_mfma_f32_16x16x32_bf16 v[190:193], v[194:197], v[28:31], v[190:193]
	v_mul_f32_e32 v198, 0xbfb8aa3b, v198
	v_mul_f32_e32 v199, 0xbfb8aa3b, v199
	v_exp_f32_e32 v198, v198
	v_exp_f32_e32 v199, v199
	ds_write2_b32 v204, v203, v88 offset0:192 offset1:208
	s_nop 2
	v_add_f32_e32 v190, v118, v190
	v_mul_f32_e32 v190, 0xbfb8aa3b, v190
	v_add_f32_e32 v191, v118, v191
	v_add_f32_e32 v88, 1.0, v198
	v_add_f32_e32 v198, 1.0, v199
	v_add_f32_e32 v199, v117, v200
	v_exp_f32_e32 v190, v190
	v_mul_f32_e32 v191, 0xbfb8aa3b, v191
	v_add_f32_e32 v192, v118, v192
	v_mul_f32_e32 v199, 0xbfb8aa3b, v199
	v_add_f32_e32 v200, v117, v201
	v_exp_f32_e32 v191, v191
	v_mul_f32_e32 v192, 0xbfb8aa3b, v192
	v_add_f32_e32 v193, v118, v193
	v_exp_f32_e32 v199, v199
	v_mul_f32_e32 v200, 0xbfb8aa3b, v200
	v_exp_f32_e32 v192, v192
	v_mul_f32_e32 v193, 0xbfb8aa3b, v193
	v_exp_f32_e32 v200, v200
	v_exp_f32_e32 v193, v193
	v_add_f32_e32 v190, 1.0, v190
	v_rcp_f32_e32 v88, v88
	v_rcp_f32_e32 v190, v190
	v_add_f32_e32 v191, 1.0, v191
	v_rcp_f32_e32 v198, v198
	v_add_f32_e32 v199, 1.0, v199
	v_rcp_f32_e32 v191, v191
	v_add_f32_e32 v192, 1.0, v192
	v_rcp_f32_e32 v199, v199
	v_add_f32_e32 v200, 1.0, v200
	v_rcp_f32_e32 v192, v192
	v_add_f32_e32 v193, 1.0, v193
	v_rcp_f32_e32 v194, v200
	v_rcp_f32_e32 v193, v193
	ds_write2_b32 v204, v88, v190 offset0:32 offset1:48
	ds_write2_b32 v204, v198, v191 offset0:96 offset1:112
	ds_write2_b32 v204, v199, v192 offset0:160 offset1:176
	ds_write2_b32 v204, v194, v193 offset0:224 offset1:240
.LBB0_1287:
	s_waitcnt vmcnt(0)
	s_add_i32 vcc_lo, s55, -1
	s_cmpk_gt_u32 vcc_lo, 0x3ff
	s_cbranch_scc1 .Lmy_w5_skA
	v_mov_b32_e32 v98, v233
	v_mov_b32_e32 v103, v229
	v_mov_b32_e32 v107, v228
	v_mov_b32_e32 v111, v227
	v_mov_b32_e32 v113, v226
	v_mov_b32_e32 v91, v229
	v_mov_b32_e32 v93, v227
	v_mov_b32_e32 v99, v237
	v_mov_b32_e32 v100, v232
	v_mov_b32_e32 v101, v236
	v_mov_b32_e32 v104, v231
	v_mov_b32_e32 v105, v235
	v_mov_b32_e32 v108, v230
	v_mov_b32_e32 v109, v234
	v_mov_b32_e32 v102, v241
	v_mov_b32_e32 v106, v240
	v_mov_b32_e32 v110, v239
	v_mov_b32_e32 v112, v238
	v_mov_b32_e32 v94, v233
	v_mov_b32_e32 v95, v237
	v_mov_b32_e32 v83, v236
	v_mov_b32_e32 v96, v231
	v_mov_b32_e32 v97, v235
	v_mov_b32_e32 v81, v234
	v_mov_b32_e32 v90, v241
	v_mov_b32_e32 v87, v228
	v_mov_b32_e32 v92, v239
	v_mov_b32_e32 v85, v226
	v_mov_b32_e32 v80, v230
	v_mov_b32_e32 v82, v232
	v_mov_b32_e32 v84, v238
	v_mov_b32_e32 v86, v240
.Lmy_w5_skA:
	s_add_i32 s8, s55, -4
	v_cndmask_b32_e64 v88, 0, 1, s[14:15]
	s_cmp_lt_i32 s8, 0
	v_cmp_ne_u32_e64 s[8:9], 1, v88
	s_cbranch_scc1 .LBB0_1300
	s_and_b64 s[10:11], s[0:1], exec
	s_cselect_b32 s77, s57, s66
	s_cmpk_lt_u32 s77, 0x3fff
	s_cselect_b64 s[10:11], -1, 0
	v_cndmask_b32_e64 v190, 0, 1.0, s[10:11]
	v_lshlrev_b32_e32 v191, 16, v143
	v_lshlrev_b32_e32 v192, 16, v149
	v_lshlrev_b32_e32 v88, 16, v140
	v_fmac_f32_e32 v191, v190, v192
	v_fma_f32 v191, v191, 0.5, -v88
	v_lshlrev_b32_e32 v192, 16, v144
	v_lshlrev_b32_e32 v193, 16, v151
	v_fmac_f32_e32 v88, v123, v191
	v_lshlrev_b32_e32 v191, 16, v141
	v_fmac_f32_e32 v192, v190, v193
	v_fma_f32 v192, v192, 0.5, -v191
	v_lshlrev_b32_e32 v193, 16, v147
	v_lshlrev_b32_e32 v194, 16, v157
	v_fmac_f32_e32 v191, v124, v192
	v_lshlrev_b32_e32 v192, 16, v142
	v_fmac_f32_e32 v193, v190, v194
	v_fma_f32 v190, v193, 0.5, -v192
	v_mul_f32_e32 v194, v120, v191
	v_fmac_f32_e32 v192, v125, v190
	v_mul_f32_e32 v190, v194, v194
	v_mov_b32_e32 v195, 0
	ds_read_b32 v193, v129 offset:16640
	v_mov_b32_dpp v190, v190 quad_perm:[1,0,3,2] row_mask:0xf bank_mask:0xf bound_ctrl:1
	v_fmac_f32_e32 v190, v194, v194
	s_and_b64 vcc, exec, s[8:9]
	s_nop 0
	v_add_f32_dpp v190, v190, v190 quad_perm:[2,3,0,1] row_mask:0xf bank_mask:0xf bound_ctrl:1
	s_nop 1
	v_add_f32_dpp v190, v190, v190 row_half_mirror row_mask:0xf bank_mask:0xf bound_ctrl:1
	s_nop 1
	v_add_f32_dpp v190, v190, v190 row_mirror row_mask:0xf bank_mask:0xf bound_ctrl:1
	s_nop 1
	v_mov_b32_dpp v195, v190 row_bcast:15 row_mask:0xa bank_mask:0xf
	v_add_f32_e32 v190, v190, v195
	v_mov_b32_e32 v195, 0
	s_nop 1
	v_mov_b32_dpp v195, v190 row_bcast:31 row_mask:0xc bank_mask:0xf
	v_add_f32_e32 v190, v190, v195
	s_nop 0
	v_readlane_b32 s10, v190, 63
	s_nop 1
	v_max_f32_e64 v190, s10, s10
	v_max_f32_e32 v190, 0x179abe15, v190
	v_rsq_f32_e32 v195, v190
	s_waitcnt lgkmcnt(0)
	v_add_f32_e32 v190, -1.0, v193
	v_fma_f32 v190, v121, v190, 1.0
	v_mul_f32_e32 v190, v191, v190
	v_mul_f32_e32 v191, v194, v195
	v_mul_f32_e32 v193, v193, v191
	ds_write2st64_b32 v129, v191, v193 offset0:165 offset1:166
	ds_write2st64_b32 v129, v190, v88 offset0:167 offset1:168
	ds_write_b32 v129, v192 offset:43264
	s_cbranch_vccnz .LBB0_1292
	v_mul_f32_e32 v88, v88, v190
	v_mul_f32_e32 v190, v122, v88
	s_nop 1
	v_mov_b32_dpp v190, v190 quad_perm:[1,0,3,2] row_mask:0xf bank_mask:0xf bound_ctrl:1
	v_fmac_f32_e32 v190, v122, v88
	s_nop 1
	v_add_f32_dpp v88, v190, v190 quad_perm:[2,3,0,1] row_mask:0xf bank_mask:0xf bound_ctrl:1
	v_mov_b32_e32 v190, 0
	s_nop 0
	v_add_f32_dpp v88, v88, v88 row_half_mirror row_mask:0xf bank_mask:0xf bound_ctrl:1
	s_nop 1
	v_add_f32_dpp v88, v88, v88 row_mirror row_mask:0xf bank_mask:0xf bound_ctrl:1
	s_nop 1
	v_mov_b32_dpp v190, v88 row_bcast:15 row_mask:0xa bank_mask:0xf
	v_add_f32_e32 v88, v88, v190
	v_mov_b32_e32 v190, 0
	s_nop 1
	v_mov_b32_dpp v190, v88 row_bcast:31 row_mask:0xc bank_mask:0xf
	v_add_f32_e32 v88, v88, v190
	s_nop 0
	v_readlane_b32 s80, v88, 63
	s_and_saveexec_b64 s[10:11], s[4:5]
	s_cbranch_execz .LBB0_1291
	s_lshl_b32 s77, s77, 7
	s_add_i32 s77, s77, s60
	v_mov_b32_e32 v88, s77
	v_mov_b32_e32 v190, s80
	global_store_dword v88, v190, s[24:25]

.LBB0_1296:
	s_add_i32 s77, s57, 2
	s_add_i32 s80, s66, -2
	s_and_b64 s[10:11], s[0:1], exec
	s_cselect_b32 s77, s77, s80
	s_cmpk_lt_u32 s77, 0x3fff
	s_cselect_b64 s[10:11], -1, 0
	v_cndmask_b32_e64 v190, 0, 1.0, s[10:11]
	v_lshlrev_b32_e32 v191, 16, v181
	v_lshlrev_b32_e32 v192, 16, v185
	v_lshlrev_b32_e32 v88, 16, v178
	v_fmac_f32_e32 v191, v190, v192
	v_fma_f32 v191, v191, 0.5, -v88
	v_lshlrev_b32_e32 v192, 16, v182
	v_lshlrev_b32_e32 v193, 16, v184
	v_fmac_f32_e32 v88, v123, v191
	v_lshlrev_b32_e32 v191, 16, v179
	v_fmac_f32_e32 v192, v190, v193
	v_fma_f32 v192, v192, 0.5, -v191
	v_lshlrev_b32_e32 v193, 16, v183
	v_lshlrev_b32_e32 v194, 16, v186
	v_fmac_f32_e32 v191, v124, v192
	v_lshlrev_b32_e32 v192, 16, v180
	v_fmac_f32_e32 v193, v190, v194
	v_fma_f32 v190, v193, 0.5, -v192
	v_mul_f32_e32 v194, v120, v191
	v_fmac_f32_e32 v192, v125, v190
	v_mul_f32_e32 v190, v194, v194
	v_mov_b32_e32 v195, 0
	ds_read_b32 v193, v129 offset:17152
	v_mov_b32_dpp v190, v190 quad_perm:[1,0,3,2] row_mask:0xf bank_mask:0xf bound_ctrl:1
	v_fmac_f32_e32 v190, v194, v194
	s_andn2_b64 vcc, exec, s[44:45]
	s_nop 0
	v_add_f32_dpp v190, v190, v190 quad_perm:[2,3,0,1] row_mask:0xf bank_mask:0xf bound_ctrl:1
	s_nop 1
	v_add_f32_dpp v190, v190, v190 row_half_mirror row_mask:0xf bank_mask:0xf bound_ctrl:1
	s_nop 1
	v_add_f32_dpp v190, v190, v190 row_mirror row_mask:0xf bank_mask:0xf bound_ctrl:1
	s_nop 1
	v_mov_b32_dpp v195, v190 row_bcast:15 row_mask:0xa bank_mask:0xf
	v_add_f32_e32 v190, v190, v195
	v_mov_b32_e32 v195, 0
	s_nop 1
	v_mov_b32_dpp v195, v190 row_bcast:31 row_mask:0xc bank_mask:0xf
	v_add_f32_e32 v190, v190, v195
	s_nop 0
	v_readlane_b32 s10, v190, 63
	s_nop 1
	v_max_f32_e64 v190, s10, s10
	v_max_f32_e32 v190, 0x179abe15, v190
	v_rsq_f32_e32 v195, v190
	s_waitcnt lgkmcnt(0)
	v_add_f32_e32 v190, -1.0, v193
	v_fma_f32 v190, v121, v190, 1.0
	v_mul_f32_e32 v190, v191, v190
	v_mul_f32_e32 v191, v194, v195
	v_mul_f32_e32 v193, v193, v191
	ds_write2st64_b32 v129, v191, v193 offset0:175 offset1:176
	ds_write2st64_b32 v129, v190, v88 offset0:177 offset1:178
	ds_write_b32 v129, v192 offset:45824
	s_cbranch_vccnz .LBB0_1300
	v_mul_f32_e32 v88, v88, v190
	v_mul_f32_e32 v190, v122, v88
	s_nop 1
	v_mov_b32_dpp v190, v190 quad_perm:[1,0,3,2] row_mask:0xf bank_mask:0xf bound_ctrl:1
	v_fmac_f32_e32 v190, v122, v88
	s_nop 1
	v_add_f32_dpp v88, v190, v190 quad_perm:[2,3,0,1] row_mask:0xf bank_mask:0xf bound_ctrl:1
	v_mov_b32_e32 v190, 0
	s_nop 0
	v_add_f32_dpp v88, v88, v88 row_half_mirror row_mask:0xf bank_mask:0xf bound_ctrl:1
	s_nop 1
	v_add_f32_dpp v88, v88, v88 row_mirror row_mask:0xf bank_mask:0xf bound_ctrl:1
	s_nop 1
	v_mov_b32_dpp v190, v88 row_bcast:15 row_mask:0xa bank_mask:0xf
	v_add_f32_e32 v88, v88, v190
	v_mov_b32_e32 v190, 0
	s_nop 1
	v_mov_b32_dpp v190, v88 row_bcast:31 row_mask:0xc bank_mask:0xf
	v_add_f32_e32 v88, v88, v190
	s_nop 0
	v_readlane_b32 s80, v88, 63
	s_and_saveexec_b64 s[10:11], s[4:5]
	s_cbranch_execz .LBB0_1299
	s_lshl_b32 s77, s77, 7
	s_add_i32 s77, s77, s60
	v_mov_b32_e32 v88, s77
	v_mov_b32_e32 v190, s80
	global_store_dword v88, v190, s[24:25]

.LBB0_1300:
	s_waitcnt lgkmcnt(0)
	s_barrier
	s_cmpk_gt_u32 s55, 0x3ff
	s_cbranch_scc1 .LBB0_1302
	v_add3_u32 v48, v114, s57, 47
	v_subrev_u32_e32 v49, 47, v189
	v_cndmask_b32_e64 v50, v49, v48, s[0:1]
	v_mul_lo_u32 v48, v50, s56
	v_cmp_eq_u32_e32 vcc, 0, v50
	v_add_lshl_u32 v88, v48, v119, 1
	v_mov_b32_e32 v51, v89
	v_cndmask_b32_e64 v48, v126, 0, vcc
	v_cmp_gt_u32_e32 vcc, s54, v50
	v_add_u32_e32 v64, v88, v48
	v_lshl_add_u64 v[48:49], s[72:73], 0, v[88:89]
	v_cndmask_b32_e32 v50, 0, v127, vcc
	v_lshl_add_u64 v[68:69], v[48:49], 0, v[50:51]
	global_load_dwordx4 v[48:51], v64, s[72:73]
	global_load_dwordx4 v[52:55], v[68:69], off
	global_load_dwordx4 v[56:59], v88, s[72:73]
	global_load_dwordx4 v[60:63], v88, s[72:73] offset:64
	v_add_u32_e32 v64, 64, v64
	global_load_dwordx4 v[64:67], v64, s[72:73]
	s_nop 0
	global_load_dwordx4 v[68:71], v[68:69], off offset:64
.LBB0_1302:
	v_cndmask_b32_e64 v88, 0, 1, s[52:53]
	v_cmp_ne_u32_e64 s[10:11], 1, v88
	s_andn2_b64 vcc, exec, s[52:53]
	s_cbranch_vccnz .LBB0_1304
	s_add_i32 s77, s57, 32
	s_sub_i32 s80, s66, 32
	s_and_b64 s[52:53], s[0:1], exec
	s_cselect_b32 s52, s77, s80
	s_mulk_i32 s52, 0xe00
	s_add_i32 s77, s57, 33
	s_sub_i32 s80, s66, 33
	v_add_lshl_u32 v88, s52, v128, 1
	s_and_b64 s[52:53], s[0:1], exec
	s_cselect_b32 s52, s77, s80
	s_mulk_i32 s52, 0xe00
	s_add_i32 s77, s57, 34
	s_sub_i32 s80, s66, 34
	v_add_lshl_u32 v176, s52, v128, 1
	s_and_b64 s[52:53], s[0:1], exec
	s_cselect_b32 s52, s77, s80
	s_mulk_i32 s52, 0xe00
	v_add_u32_e32 v144, 0xffffe400, v88
	v_add_u32_e32 v151, 0x1c00, v88
	v_add_u32_e32 v140, 0xfffff800, v88
	v_add_u32_e32 v142, 0x800, v88
	v_add_u32_e32 v143, 0xffffdc00, v88
	v_add_u32_e32 v147, 0xffffec00, v88
	v_add_u32_e32 v149, 0x1400, v88
	v_add_lshl_u32 v183, s52, v128, 1
	global_load_ushort v140, v140, s[72:73]
	s_nop 0
	global_load_ushort v141, v88, s[72:73]
	s_nop 0
	global_load_ushort v142, v142, s[72:73]
	s_nop 0
	global_load_ushort v143, v143, s[72:73]
	s_nop 0
	global_load_ushort v144, v144, s[72:73]
	s_nop 0
	global_load_ushort v147, v147, s[72:73]
	s_nop 0
	global_load_ushort v149, v149, s[72:73]
	s_nop 0
	global_load_ushort v151, v151, s[72:73]
	v_add_u32_e32 v88, 0x2400, v88
	v_add_u32_e32 v163, 0xffffe400, v176
	v_add_u32_e32 v167, 0x1c00, v176
	v_add_u32_e32 v158, 0xfffff800, v176
	v_add_u32_e32 v160, 0x800, v176
	v_add_u32_e32 v161, 0xffffdc00, v176
	v_add_u32_e32 v164, 0xffffec00, v176
	v_add_u32_e32 v177, 0x1400, v176
	v_add_u32_e32 v182, 0xffffe400, v183
	v_add_u32_e32 v184, 0x1c00, v183
	v_add_u32_e32 v178, 0xfffff800, v183
	v_add_u32_e32 v180, 0x800, v183
	v_add_u32_e32 v181, 0xffffdc00, v183
	global_load_ushort v157, v88, s[72:73]
	s_nop 0
	global_load_ushort v158, v158, s[72:73]
	s_nop 0
	global_load_ushort v159, v176, s[72:73]
	s_nop 0
	global_load_ushort v160, v160, s[72:73]
	s_nop 0
	global_load_ushort v161, v161, s[72:73]
	s_nop 0
	global_load_ushort v163, v163, s[72:73]
	s_nop 0
	global_load_ushort v164, v164, s[72:73]
	s_nop 0
	global_load_ushort v167, v167, s[72:73]
	v_add_u32_e32 v88, 0x2400, v176
	global_load_ushort v176, v177, s[72:73]
	s_nop 0
	global_load_ushort v177, v88, s[72:73]
	s_nop 0
	global_load_ushort v178, v178, s[72:73]
	s_nop 0
	global_load_ushort v179, v183, s[72:73]
	s_nop 0
	global_load_ushort v180, v180, s[72:73]
	s_nop 0
	global_load_ushort v181, v181, s[72:73]
	s_nop 0
	global_load_ushort v182, v182, s[72:73]
	s_nop 0
	global_load_ushort v184, v184, s[72:73]
	v_add_u32_e32 v185, 0xffffec00, v183
	v_add_u32_e32 v186, 0x1400, v183
	v_add_u32_e32 v88, 0x2400, v183
	global_load_ushort v183, v185, s[72:73]
	s_nop 0
	global_load_ushort v185, v186, s[72:73]
	s_nop 0
	global_load_ushort v186, v88, s[72:73]
.LBB0_1304:
	s_and_b64 vcc, exec, s[10:11]
	s_cbranch_vccnz .LBB0_1306
	v_cndmask_b32_e64 v88, v188, v187, s[0:1]
	v_lshlrev_b32_e32 v187, 16, v113
	v_and_b32_e32 v191, s0, v113
	v_and_b32_e32 v190, 0xffff0000, v112
	v_pk_mov_b32 v[190:191], v[186:187], v[190:191] op_sel:[1,0]
	v_lshlrev_b32_e32 v187, 16, v111
	v_and_b32_e32 v195, s0, v111
	v_and_b32_e32 v194, 0xffff0000, v110
	v_pk_mov_b32 v[194:195], v[186:187], v[194:195] op_sel:[1,0]
	v_lshlrev_b32_e32 v187, 16, v107
	v_and_b32_e32 v199, s0, v107
	v_and_b32_e32 v198, 0xffff0000, v106
	v_pk_mov_b32 v[198:199], v[186:187], v[198:199] op_sel:[1,0]
	v_lshlrev_b32_e32 v187, 16, v103
	v_and_b32_e32 v203, s0, v103
	v_and_b32_e32 v202, 0xffff0000, v102
	v_pk_mov_b32 v[202:203], v[186:187], v[202:203] op_sel:[1,0]
	v_lshlrev_b32_e32 v187, 16, v109
	v_and_b32_e32 v207, s0, v109
	v_and_b32_e32 v206, 0xffff0000, v108
	v_cmp_eq_u32_e32 vcc, 0, v88
	v_pk_mov_b32 v[206:207], v[186:187], v[206:207] op_sel:[1,0]
	v_lshlrev_b32_e32 v187, 16, v105
	v_and_b32_e32 v211, s0, v105
	v_and_b32_e32 v210, 0xffff0000, v104
	v_cndmask_b32_e64 v225, 1.0, 0, vcc
	v_cmp_gt_u32_e32 vcc, s54, v88
	v_pk_mov_b32 v[210:211], v[186:187], v[210:211] op_sel:[1,0]
	v_lshlrev_b32_e32 v187, 16, v101
	v_and_b32_e32 v215, s0, v101
	v_and_b32_e32 v217, 0xffff0000, v101
	v_lshlrev_b32_e32 v101, 16, v99
	v_and_b32_e32 v221, s0, v99
	v_and_b32_e32 v220, 0xffff0000, v98
	v_cndmask_b32_e64 v224, 0, 1.0, vcc
	v_lshlrev_b32_e32 v110, 16, v110
	v_and_b32_e32 v111, 0xffff0000, v111
	v_and_b32_e32 v214, 0xffff0000, v100
	v_lshlrev_b32_e32 v216, 16, v100
	v_pk_mov_b32 v[220:221], v[100:101], v[220:221] op_sel:[1,0]
	v_pk_mul_f32 v[100:101], v[224:225], v[194:195] op_sel:[1,0] op_sel_hi:[0,1]
	v_lshlrev_b32_e32 v106, 16, v106
	v_and_b32_e32 v107, 0xffff0000, v107
	v_pk_fma_f32 v[100:101], v[224:225], v[110:111], v[100:101]
	v_pk_mul_f32 v[110:111], v[224:225], v[198:199] op_sel:[1,0] op_sel_hi:[0,1]
	v_lshlrev_b32_e32 v112, 16, v112
	v_and_b32_e32 v113, 0xffff0000, v113
	v_lshlrev_b32_e32 v102, 16, v102
	v_and_b32_e32 v103, 0xffff0000, v103
	v_lshlrev_b32_e32 v222, 16, v98
	v_and_b32_e32 v223, 0xffff0000, v99
	v_pk_mul_f32 v[98:99], v[224:225], v[190:191] op_sel:[1,0] op_sel_hi:[0,1]
	v_pk_fma_f32 v[106:107], v[224:225], v[106:107], v[110:111]
	v_pk_mul_f32 v[110:111], v[224:225], v[202:203] op_sel:[1,0] op_sel_hi:[0,1]
	v_lshlrev_b32_e32 v188, 16, v72
	v_and_b32_e32 v189, 0xffff0000, v72
	v_lshlrev_b32_e32 v192, 16, v73
	v_and_b32_e32 v193, 0xffff0000, v73
	v_lshlrev_b32_e32 v196, 16, v74
	v_and_b32_e32 v197, 0xffff0000, v74
	v_lshlrev_b32_e32 v200, 16, v75
	v_and_b32_e32 v201, 0xffff0000, v75
	v_pk_fma_f32 v[98:99], v[224:225], v[112:113], v[98:99]
	v_pk_fma_f32 v[102:103], v[224:225], v[102:103], v[110:111]
	v_pk_fma_f32 v[98:99], v[98:99], 0.5, v[188:189] op_sel_hi:[1,0,1] neg_lo:[0,0,1] neg_hi:[0,0,1]
	v_pk_fma_f32 v[100:101], v[100:101], 0.5, v[192:193] op_sel_hi:[1,0,1] neg_lo:[0,0,1] neg_hi:[0,0,1]
	v_pk_fma_f32 v[106:107], v[106:107], 0.5, v[196:197] op_sel_hi:[1,0,1] neg_lo:[0,0,1] neg_hi:[0,0,1]
	v_pk_fma_f32 v[102:103], v[102:103], 0.5, v[200:201] op_sel_hi:[1,0,1] neg_lo:[0,0,1] neg_hi:[0,0,1]
	v_pk_fma_f32 v[98:99], v[32:33], v[98:99], v[188:189]
	v_pk_fma_f32 v[100:101], v[34:35], v[100:101], v[192:193]
	v_pk_fma_f32 v[106:107], v[36:37], v[106:107], v[196:197]
	v_pk_fma_f32 v[102:103], v[38:39], v[102:103], v[200:201]
	v_lshlrev_b32_e32 v108, 16, v108
	v_and_b32_e32 v109, 0xffff0000, v109
	v_lshlrev_b32_e32 v104, 16, v104
	v_and_b32_e32 v105, 0xffff0000, v105
	v_pk_mov_b32 v[214:215], v[186:187], v[214:215] op_sel:[1,0]
	v_cvt_pk_bf16_f32 v98, v98, v99
	v_cvt_pk_bf16_f32 v99, v100, v101
	v_cvt_pk_bf16_f32 v100, v106, v107
	v_cvt_pk_bf16_f32 v101, v102, v103
	v_pk_mul_f32 v[102:103], v[224:225], v[206:207] op_sel:[1,0] op_sel_hi:[0,1]
	v_pk_mul_f32 v[106:107], v[224:225], v[210:211] op_sel:[1,0] op_sel_hi:[0,1]
	v_pk_fma_f32 v[102:103], v[224:225], v[108:109], v[102:103]
	v_pk_fma_f32 v[104:105], v[224:225], v[104:105], v[106:107]
	v_pk_mul_f32 v[106:107], v[224:225], v[214:215] op_sel:[1,0] op_sel_hi:[0,1]
	v_pk_mul_f32 v[108:109], v[224:225], v[220:221] op_sel:[1,0] op_sel_hi:[0,1]
	v_lshlrev_b32_e32 v204, 16, v76
	v_and_b32_e32 v205, 0xffff0000, v76
	v_lshlrev_b32_e32 v208, 16, v77
	v_and_b32_e32 v209, 0xffff0000, v77
	v_lshlrev_b32_e32 v212, 16, v78
	v_and_b32_e32 v213, 0xffff0000, v78
	v_lshlrev_b32_e32 v218, 16, v79
	v_and_b32_e32 v219, 0xffff0000, v79
	v_pk_fma_f32 v[106:107], v[224:225], v[216:217], v[106:107]
	v_pk_fma_f32 v[108:109], v[224:225], v[222:223], v[108:109]
	v_pk_fma_f32 v[102:103], v[102:103], 0.5, v[204:205] op_sel_hi:[1,0,1] neg_lo:[0,0,1] neg_hi:[0,0,1]
	v_pk_fma_f32 v[104:105], v[104:105], 0.5, v[208:209] op_sel_hi:[1,0,1] neg_lo:[0,0,1] neg_hi:[0,0,1]
	v_pk_fma_f32 v[106:107], v[106:107], 0.5, v[212:213] op_sel_hi:[1,0,1] neg_lo:[0,0,1] neg_hi:[0,0,1]
	v_pk_fma_f32 v[108:109], v[108:109], 0.5, v[218:219] op_sel_hi:[1,0,1] neg_lo:[0,0,1] neg_hi:[0,0,1]
	v_pk_fma_f32 v[102:103], v[40:41], v[102:103], v[204:205]
	v_pk_fma_f32 v[104:105], v[42:43], v[104:105], v[208:209]
	v_pk_fma_f32 v[106:107], v[44:45], v[106:107], v[212:213]
	v_pk_fma_f32 v[110:111], v[46:47], v[108:109], v[218:219]
	v_cvt_pk_bf16_f32 v102, v102, v103
	v_cvt_pk_bf16_f32 v103, v104, v105
	v_cvt_pk_bf16_f32 v104, v106, v107
	v_cvt_pk_bf16_f32 v105, v110, v111
	v_mfma_f32_16x16x32_bf16 v[106:109], v[98:101], v[0:3], 0
	s_nop 0
	v_mfma_f32_16x16x32_bf16 v[106:109], v[102:105], v[4:7], v[106:109]
	v_mfma_f32_16x16x32_bf16 v[110:113], v[98:101], v[8:11], 0
	s_nop 6
	v_add_f32_e32 v88, v115, v106
	v_add_f32_e32 v106, v115, v107
	v_mul_f32_e32 v106, 0xbfb8aa3b, v106
	v_exp_f32_e32 v106, v106
	v_add_f32_e32 v107, v115, v108
	v_mul_f32_e32 v107, 0xbfb8aa3b, v107
	v_exp_f32_e32 v107, v107
	v_add_f32_e32 v106, 1.0, v106
	v_rcp_f32_e32 v187, v106
	v_add_f32_e32 v106, v115, v109
	v_mul_f32_e32 v106, 0xbfb8aa3b, v106
	v_add_f32_e32 v188, 1.0, v107
	v_exp_f32_e32 v189, v106
	v_mfma_f32_16x16x32_bf16 v[106:109], v[102:105], v[12:15], v[110:113]
	v_mul_f32_e32 v88, 0xbfb8aa3b, v88
	v_exp_f32_e32 v88, v88
	s_nop 0
	v_add_u32_e32 v112, 0x4000, v131
	v_rcp_f32_e32 v110, v188
	s_nop 2
	v_add_f32_e32 v106, v116, v106
	v_mul_f32_e32 v106, 0xbfb8aa3b, v106
	v_exp_f32_e32 v106, v106
	v_add_f32_e32 v108, v116, v108
	v_add_f32_e32 v88, 1.0, v88
	v_mul_f32_e32 v108, 0xbfb8aa3b, v108
	v_add_f32_e32 v106, 1.0, v106
	v_rcp_f32_e32 v88, v88
	v_rcp_f32_e32 v106, v106
	v_exp_f32_e32 v108, v108
	v_add_f32_e32 v107, v116, v107
	v_mul_f32_e32 v107, 0xbfb8aa3b, v107
	v_exp_f32_e32 v107, v107
	ds_write2_b32 v112, v88, v106 offset1:16
	v_add_f32_e32 v106, 1.0, v108
	v_rcp_f32_e32 v113, v106
	v_add_f32_e32 v106, v116, v109
	v_mul_f32_e32 v106, 0xbfb8aa3b, v106
	v_add_f32_e32 v88, 1.0, v107
	v_exp_f32_e32 v188, v106
	v_mfma_f32_16x16x32_bf16 v[106:109], v[98:101], v[16:19], 0
	v_rcp_f32_e32 v88, v88
	v_add_f32_e32 v111, 1.0, v189
	v_rcp_f32_e32 v111, v111
	v_mfma_f32_16x16x32_bf16 v[106:109], v[102:105], v[20:23], v[106:109]
	ds_write2_b32 v112, v187, v88 offset0:64 offset1:80
	v_add_f32_e32 v88, 1.0, v188
	v_rcp_f32_e32 v88, v88
	v_mfma_f32_16x16x32_bf16 v[98:101], v[98:101], v[24:27], 0
	ds_write2_b32 v112, v110, v113 offset0:128 offset1:144
	s_nop 2
	v_add_f32_e32 v106, v117, v106
	v_add_f32_e32 v107, v117, v107
	v_mfma_f32_16x16x32_bf16 v[98:101], v[102:105], v[28:31], v[98:101]
	v_mul_f32_e32 v106, 0xbfb8aa3b, v106
	v_mul_f32_e32 v107, 0xbfb8aa3b, v107
	v_exp_f32_e32 v106, v106
	v_exp_f32_e32 v107, v107
	ds_write2_b32 v112, v111, v88 offset0:192 offset1:208
	s_nop 2
	v_add_f32_e32 v98, v118, v98
	v_mul_f32_e32 v98, 0xbfb8aa3b, v98
	v_add_f32_e32 v99, v118, v99
	v_add_f32_e32 v88, 1.0, v106
	v_add_f32_e32 v106, 1.0, v107
	v_add_f32_e32 v107, v117, v108
	v_exp_f32_e32 v98, v98
	v_mul_f32_e32 v99, 0xbfb8aa3b, v99
	v_add_f32_e32 v100, v118, v100
	v_mul_f32_e32 v107, 0xbfb8aa3b, v107
	v_add_f32_e32 v108, v117, v109
	v_exp_f32_e32 v99, v99
	v_mul_f32_e32 v100, 0xbfb8aa3b, v100
	v_add_f32_e32 v101, v118, v101
	v_exp_f32_e32 v107, v107
	v_mul_f32_e32 v108, 0xbfb8aa3b, v108
	v_exp_f32_e32 v100, v100
	v_mul_f32_e32 v101, 0xbfb8aa3b, v101
	v_exp_f32_e32 v108, v108
	v_exp_f32_e32 v101, v101
	v_add_f32_e32 v98, 1.0, v98
	v_rcp_f32_e32 v88, v88
	v_rcp_f32_e32 v98, v98
	v_add_f32_e32 v99, 1.0, v99
	v_rcp_f32_e32 v106, v106
	v_add_f32_e32 v107, 1.0, v107
	v_rcp_f32_e32 v99, v99
	v_add_f32_e32 v100, 1.0, v100
	v_rcp_f32_e32 v107, v107
	v_add_f32_e32 v108, 1.0, v108
	v_rcp_f32_e32 v100, v100
	v_add_f32_e32 v101, 1.0, v101
	v_rcp_f32_e32 v102, v108
	v_rcp_f32_e32 v101, v101
	ds_write2_b32 v112, v88, v98 offset0:32 offset1:48
	ds_write2_b32 v112, v106, v99 offset0:96 offset1:112
	ds_write2_b32 v112, v107, v100 offset0:160 offset1:176
	ds_write2_b32 v112, v102, v101 offset0:224 offset1:240
.LBB0_1306:
	s_waitcnt vmcnt(0)
	s_and_b64 vcc, exec, s[6:7]
	s_cbranch_vccnz .LBB0_1279
	v_lshlrev_b32_e32 v98, 16, v135
	v_lshlrev_b32_e32 v99, 16, v138
	v_lshlrev_b32_e32 v88, 16, v132
	v_add_f32_e32 v98, v98, v99
	v_fma_f32 v98, v98, 0.5, -v88
	v_lshlrev_b32_e32 v99, 16, v136
	v_lshlrev_b32_e32 v100, 16, v139
	v_fmac_f32_e32 v88, v123, v98
	v_lshlrev_b32_e32 v98, 16, v133
	v_add_f32_e32 v99, v99, v100
	v_fma_f32 v99, v99, 0.5, -v98
	v_fmac_f32_e32 v98, v124, v99
	v_lshlrev_b32_e32 v100, 16, v137
	v_lshlrev_b32_e32 v101, 16, v145
	v_add_f32_e32 v100, v100, v101
	v_mul_f32_e32 v101, v120, v98
	v_mul_f32_e32 v102, v101, v101
	v_mov_b32_e32 v103, 0
	v_lshlrev_b32_e32 v99, 16, v134
	v_mov_b32_dpp v102, v102 quad_perm:[1,0,3,2] row_mask:0xf bank_mask:0xf bound_ctrl:1
	v_fmac_f32_e32 v102, v101, v101
	v_fma_f32 v100, v100, 0.5, -v99
	v_fmac_f32_e32 v99, v125, v100
	v_add_f32_dpp v102, v102, v102 quad_perm:[2,3,0,1] row_mask:0xf bank_mask:0xf bound_ctrl:1
	ds_read_b32 v100, v129 offset:12544
	s_and_b64 vcc, exec, s[8:9]
	v_add_f32_dpp v102, v102, v102 row_half_mirror row_mask:0xf bank_mask:0xf bound_ctrl:1
	s_nop 1
	v_add_f32_dpp v102, v102, v102 row_mirror row_mask:0xf bank_mask:0xf bound_ctrl:1
	s_nop 1
	v_mov_b32_dpp v103, v102 row_bcast:15 row_mask:0xa bank_mask:0xf
	v_add_f32_e32 v102, v102, v103
	v_mov_b32_e32 v103, 0
	s_nop 1
	v_mov_b32_dpp v103, v102 row_bcast:31 row_mask:0xc bank_mask:0xf
	v_add_f32_e32 v102, v102, v103
	s_waitcnt lgkmcnt(0)
	v_add_f32_e32 v103, -1.0, v100
	v_readlane_b32 s6, v102, 63
	v_fma_f32 v103, v121, v103, 1.0
	v_mul_f32_e32 v98, v98, v103
	v_max_f32_e64 v102, s6, s6
	v_max_f32_e32 v102, 0x179abe15, v102
	v_rsq_f32_e32 v102, v102
	s_nop 0
	v_mul_f32_e32 v101, v101, v102
	v_mul_f32_e32 v100, v100, v101
	ds_write2st64_b32 v129, v101, v100 offset0:85 offset1:86
	ds_write2st64_b32 v129, v98, v88 offset0:87 offset1:88
	ds_write_b32 v129, v99 offset:22784
	s_cbranch_vccnz .LBB0_1311
	v_mul_f32_e32 v88, v88, v98
	v_mul_f32_e32 v98, v122, v88
	s_nop 1
	v_mov_b32_dpp v98, v98 quad_perm:[1,0,3,2] row_mask:0xf bank_mask:0xf bound_ctrl:1
	v_fmac_f32_e32 v98, v122, v88
	s_nop 1
	v_add_f32_dpp v88, v98, v98 quad_perm:[2,3,0,1] row_mask:0xf bank_mask:0xf bound_ctrl:1
	v_mov_b32_e32 v98, 0
	s_nop 0
	v_add_f32_dpp v88, v88, v88 row_half_mirror row_mask:0xf bank_mask:0xf bound_ctrl:1
	s_nop 1
	v_add_f32_dpp v88, v88, v88 row_mirror row_mask:0xf bank_mask:0xf bound_ctrl:1
	s_nop 1
	v_mov_b32_dpp v98, v88 row_bcast:15 row_mask:0xa bank_mask:0xf
	v_add_f32_e32 v88, v88, v98
	v_mov_b32_e32 v98, 0
	s_nop 1
	v_mov_b32_dpp v98, v88 row_bcast:31 row_mask:0xc bank_mask:0xf
	v_add_f32_e32 v88, v88, v98
	s_nop 0
	v_readlane_b32 s8, v88, 63
	s_and_saveexec_b64 s[6:7], s[4:5]
	s_cbranch_execz .LBB0_1310
	s_add_i32 s9, s57, 16
	s_add_i32 s52, s66, -16
	s_and_b64 s[10:11], s[0:1], exec
	s_cselect_b32 s9, s9, s52
	s_lshl_b32 s9, s9, 7
	s_add_i32 s9, s9, s60
	v_mov_b32_e32 v88, s9
	v_mov_b32_e32 v98, s8
	global_store_dword v88, v98, s[24:25]

.LBB0_1315:
	v_lshlrev_b32_e32 v98, 16, v170
	v_lshlrev_b32_e32 v99, 16, v174
	v_lshlrev_b32_e32 v88, 16, v166
	v_add_f32_e32 v98, v98, v99
	v_fma_f32 v98, v98, 0.5, -v88
	v_lshlrev_b32_e32 v99, 16, v171
	v_lshlrev_b32_e32 v100, 16, v173
	v_fmac_f32_e32 v88, v123, v98
	v_lshlrev_b32_e32 v98, 16, v168
	v_add_f32_e32 v99, v99, v100
	v_fma_f32 v99, v99, 0.5, -v98
	v_fmac_f32_e32 v98, v124, v99
	v_lshlrev_b32_e32 v100, 16, v172
	v_lshlrev_b32_e32 v101, 16, v175
	v_add_f32_e32 v100, v100, v101
	v_mul_f32_e32 v101, v120, v98
	v_mul_f32_e32 v102, v101, v101
	v_mov_b32_e32 v103, 0
	v_lshlrev_b32_e32 v99, 16, v169
	v_mov_b32_dpp v102, v102 quad_perm:[1,0,3,2] row_mask:0xf bank_mask:0xf bound_ctrl:1
	v_fmac_f32_e32 v102, v101, v101
	v_fma_f32 v100, v100, 0.5, -v99
	v_fmac_f32_e32 v99, v125, v100
	v_add_f32_dpp v102, v102, v102 quad_perm:[2,3,0,1] row_mask:0xf bank_mask:0xf bound_ctrl:1
	ds_read_b32 v100, v129 offset:13056
	s_andn2_b64 vcc, exec, s[44:45]
	v_add_f32_dpp v102, v102, v102 row_half_mirror row_mask:0xf bank_mask:0xf bound_ctrl:1
	s_nop 1
	v_add_f32_dpp v102, v102, v102 row_mirror row_mask:0xf bank_mask:0xf bound_ctrl:1
	s_nop 1
	v_mov_b32_dpp v103, v102 row_bcast:15 row_mask:0xa bank_mask:0xf
	v_add_f32_e32 v102, v102, v103
	v_mov_b32_e32 v103, 0
	s_nop 1
	v_mov_b32_dpp v103, v102 row_bcast:31 row_mask:0xc bank_mask:0xf
	v_add_f32_e32 v102, v102, v103
	s_waitcnt lgkmcnt(0)
	v_add_f32_e32 v103, -1.0, v100
	v_readlane_b32 s6, v102, 63
	v_fma_f32 v103, v121, v103, 1.0
	v_mul_f32_e32 v98, v98, v103
	v_max_f32_e64 v102, s6, s6
	v_max_f32_e32 v102, 0x179abe15, v102
	v_rsq_f32_e32 v102, v102
	s_nop 0
	v_mul_f32_e32 v101, v101, v102
	v_mul_f32_e32 v100, v100, v101
	ds_write2st64_b32 v129, v101, v100 offset0:95 offset1:96
	ds_write2st64_b32 v129, v98, v88 offset0:97 offset1:98
	ds_write_b32 v129, v99 offset:25344
	s_cbranch_vccnz .LBB0_1279
	v_mul_f32_e32 v88, v88, v98
	v_mul_f32_e32 v98, v122, v88
	s_nop 1
	v_mov_b32_dpp v98, v98 quad_perm:[1,0,3,2] row_mask:0xf bank_mask:0xf bound_ctrl:1
	v_fmac_f32_e32 v98, v122, v88
	s_nop 1
	v_add_f32_dpp v88, v98, v98 quad_perm:[2,3,0,1] row_mask:0xf bank_mask:0xf bound_ctrl:1
	v_mov_b32_e32 v98, 0
	s_nop 0
	v_add_f32_dpp v88, v88, v88 row_half_mirror row_mask:0xf bank_mask:0xf bound_ctrl:1
	s_nop 1
	v_add_f32_dpp v88, v88, v88 row_mirror row_mask:0xf bank_mask:0xf bound_ctrl:1
	s_nop 1
	v_mov_b32_dpp v98, v88 row_bcast:15 row_mask:0xa bank_mask:0xf
	v_add_f32_e32 v88, v88, v98
	v_mov_b32_e32 v98, 0
	s_nop 1
	v_mov_b32_dpp v98, v88 row_bcast:31 row_mask:0xc bank_mask:0xf
	v_add_f32_e32 v88, v88, v98
	s_nop 0
	v_readlane_b32 s8, v88, 63
	s_and_saveexec_b64 s[6:7], s[4:5]
	s_cbranch_execz .LBB0_1278
	s_add_i32 s9, s57, 18
	s_sub_i32 s52, s66, 18
	s_and_b64 s[10:11], s[0:1], exec
	s_cselect_b32 s9, s9, s52
	s_lshl_b32 s9, s9, 7
	s_add_i32 s9, s9, s60
	v_mov_b32_e32 v88, s9
	v_mov_b32_e32 v98, s8
	global_store_dword v88, v98, s[24:25]
	s_branch .LBB0_1278

; template <int NS, bool LORA, int mat> ...
;     ...
;   bf16x8 bw[4][2]; float bias[4]; float mu0[8], mu1[8];
;   const int colA = 3072 + mat * 128 + dir * 64 + fq * 8;
;   if (LORA) {
;     const u16* WT = (const u16*)(p.ws + (mat ? OFF_A2T : OFF_W2T)) + ((size_t)dir * 1024 + 64 * head + fr) * 64 + fq * 8;
; #pragma unroll
;     for (int nt = 0; nt < 4; ++nt) {
;       bw[nt][0] = *(const bf16x8*)(WT + nt * 16 * 64);
;       bw[nt][1] = *(const bf16x8*)(WT + nt * 16 * 64 + 32);
;       bias[nt] = (mat ? p.a0 : p.w0)[dir * 1024 + 64 * head + nt * 16 + fr];
;     }
; #pragma unroll
;     for (int j = 0; j < 8; ++j) { mu0[j] = p.mu_shift[colA + j]; mu1[j] = p.mu_shift[colA + 32 + j]; }
;   }
;   const int ch = 64 * head + lane;
;   const float kk_c = p.k_k[ch], ka_c = p.k_a[ch], rk_c = p.r_k[ch];
;   const float mu_r = p.mu_shift[ch], mu_k = p.mu_shift[1024 + ch], mu_v = p.mu_shift[2048 + ch];
;   uint4 la[2][6];
;   u16 rv[2][NS][9];
.LBB0_1319:
	s_andn2_saveexec_b64 s[12:13], s[48:49]
	s_cbranch_execz .LBB0_1345
	s_waitcnt vmcnt(11)
	v_and_b32_e32 v128, 15, v140
	s_waitcnt vmcnt(5)
	v_or_b32_e32 v0, s64, v128
	s_waitcnt vmcnt(4)
	v_mov_b32_e32 v1, s65
	v_lshlrev_b64 v[0:1], 7, v[0:1]
	v_lshrrev_b32_e32 v8, 4, v148
	s_waitcnt vmcnt(2)
	v_lshl_add_u64 v[2:3], s[36:37], 0, v[0:1]
	v_and_b32_e32 v0, 48, v148
	v_mov_b32_e32 v1, 0
	v_lshl_or_b32 v6, v8, 3, s63
	v_lshl_add_u64 v[2:3], v[2:3], 0, v[0:1]
	s_movk_i32 s4, 0x1000
	s_waitcnt vmcnt(1)
	v_or_b32_e32 v4, s62, v128
	global_load_dwordx4 v[18:21], v[2:3], off
	global_load_dwordx4 v[22:25], v[2:3], off offset:64
	global_load_dwordx4 v[26:29], v[2:3], off offset:2048
	global_load_dwordx4 v[30:33], v[2:3], off offset:2112
	v_add_co_u32_e32 v2, vcc, s4, v2
	v_or_b32_e32 v133, 0xc00, v6
	s_waitcnt vmcnt(4)
	v_ashrrev_i32_e32 v5, 31, v4
	v_addc_co_u32_e32 v3, vcc, 0, v3, vcc
	v_lshlrev_b32_e32 v0, 2, v133
	v_lshl_add_u64 v[4:5], v[4:5], 2, s[40:41]
	global_load_dwordx4 v[34:37], v[2:3], off
	global_load_dwordx4 v[38:41], v[2:3], off offset:64
	global_load_dwordx4 v[42:45], v[2:3], off offset:2048
	global_load_dwordx4 v[46:49], v[2:3], off offset:2112
	global_load_dword v129, v[4:5], off
	global_load_dword v130, v[4:5], off offset:64
	global_load_dword v131, v[4:5], off offset:128
	global_load_dword v132, v[4:5], off offset:192
	global_load_dwordx4 v[50:53], v0, s[38:39]
	global_load_dwordx4 v[54:57], v0, s[38:39] offset:16
	v_lshlrev_b32_e32 v0, 2, v6
	v_lshl_add_u64 v[2:3], s[38:39], 0, v[0:1]
	s_mov_b64 s[4:5], 0x3080
	v_lshl_add_u64 v[4:5], v[2:3], 0, s[4:5]
	s_movk_i32 s4, 0x3000
	v_add_co_u32_e32 v2, vcc, s4, v2
	s_movk_i32 s4, 0x2000
	s_nop 0
	v_addc_co_u32_e32 v3, vcc, 0, v3, vcc
	global_load_dwordx4 v[58:61], v[2:3], off offset:128
	global_load_dwordx4 v[62:65], v[4:5], off offset:16
	v_or_b32_e32 v2, s61, v148
	v_ashrrev_i32_e32 v3, 31, v2
	v_lshlrev_b64 v[4:5], 2, v[2:3]
	v_lshl_add_u64 v[6:7], s[50:51], 0, v[4:5]
	global_load_dword v134, v[6:7], off
	v_lshl_add_u64 v[6:7], s[16:17], 0, v[4:5]
	global_load_dword v135, v[6:7], off
	v_lshl_add_u64 v[6:7], s[18:19], 0, v[4:5]
	v_lshl_add_u64 v[4:5], s[38:39], 0, v[4:5]
	s_movk_i32 s18, 0x3fff
	global_load_dword v137, v[4:5], off
	v_add_co_u32_e32 v4, vcc, s4, v4
	v_bitop3_b32 v0, v140, s18, 15 bitop3:0x6c
	s_nop 0
	v_addc_co_u32_e32 v5, vcc, 0, v5, vcc
	v_cndmask_b32_e64 v3, v0, v128, s[0:1]
	v_mul_u32_u24_e32 v0, 0xe00, v3
	v_mov_b32_e32 v140, 0xffffe400
	v_cmp_eq_u32_e32 vcc, 0, v3
	global_load_dword v136, v[6:7], off
	global_load_dword v138, v[4:5], off offset:-4096
	global_load_dword v139, v[4:5], off
	v_add_lshl_u32 v0, v133, v0, 1
	v_cndmask_b32_e64 v4, v140, 0, vcc
	v_mov_b32_e32 v141, 0x1c00
	v_cmp_eq_u32_e32 vcc, s18, v3
	v_add_u32_e32 v9, v0, v4
	v_lshl_add_u64 v[4:5], s[72:73], 0, v[0:1]
	v_cndmask_b32_e64 v6, v141, 0, vcc
	v_mov_b32_e32 v7, v1
	v_lshl_add_u64 v[4:5], v[4:5], 0, v[6:7]
	global_load_dwordx4 v[66:69], v9, s[72:73]
	global_load_dwordx4 v[70:73], v[4:5], off
	global_load_dwordx4 v[74:77], v0, s[72:73]
	global_load_dwordx4 v[78:81], v0, s[72:73] offset:64
	v_add_u32_e32 v0, 64, v9
	global_load_dwordx4 v[82:85], v0, s[72:73]
	global_load_dwordx4 v[86:89], v[4:5], off offset:64
	v_add_u32_e32 v142, 0x400, v2
	v_lshlrev_b32_e32 v143, 10, v8
	v_mov_b32_e32 v2, v1
	v_mov_b32_e32 v3, v1
	v_mov_b32_e32 v4, v1
	v_mov_b32_e32 v5, v1
	v_mov_b32_e32 v6, v1
	v_mov_b32_e32 v8, v1
	s_cmp_eq_u32 s3, 0
	v_mov_b32_e32 v0, v1
	v_mov_b64_e32 v[16:17], v[14:15]
	s_mov_b32 s19, 0
	s_cselect_b64 s[14:15], -1, 0
	s_mov_b32 s36, 2
	s_movk_i32 s37, 0xe00
	v_lshl_add_u32 v144, v128, 2, 0
	v_lshl_add_u32 v145, v148, 2, 0
	v_cmp_eq_u32_e64 s[4:5], 0, v148
	v_sub_u32_e32 v147, 0, v128
	s_mov_b32 s40, -16
	s_movk_i32 s41, 0x400f
	s_mov_b32 s42, 0x5040100
	s_mov_b32 s43, 0xffff
	v_mov_b64_e32 v[14:15], v[12:13]
	v_mov_b64_e32 v[12:13], v[10:11]
	v_mov_b64_e32 v[10:11], v[8:9]
	v_mov_b64_e32 v[8:9], v[6:7]
	v_mov_b64_e32 v[6:7], v[4:5]
	v_mov_b64_e32 v[4:5], v[2:3]
	v_mov_b64_e32 v[2:3], v[0:1]
	s_waitcnt vmcnt(0)
	s_branch .LBB0_1323

.LBB0_1323:
	s_add_i32 s6, s36, -1
	s_cmpk_lt_u32 s6, 0x400
	v_add_u32_e32 v149, s41, v147
	s_cselect_b64 s[16:17], -1, 0
	s_cmpk_gt_u32 s6, 0x3ff
	v_add3_u32 v11, v128, s40, 32
	v_subrev_u32_e32 v148, 32, v149
	s_cbranch_scc1 .LBB0_1325
	v_cndmask_b32_e64 v90, v148, v11, s[0:1]
	v_mul_lo_u32 v0, v90, s37
	v_cmp_eq_u32_e32 vcc, 0, v90
	v_add_lshl_u32 v0, v0, v133, 1
	v_lshl_add_u64 v[16:17], s[72:73], 0, v[0:1]
	v_cndmask_b32_e64 v12, v140, 0, vcc
	v_add_u32_e32 v92, v0, v12
	v_cmp_gt_u32_e32 vcc, s18, v90
	global_load_dwordx4 v[180:183], v92, s[72:73]
	v_mov_b32_e32 v91, v1
	v_cndmask_b32_e32 v90, 0, v141, vcc
	v_lshl_add_u64 v[16:17], v[16:17], 0, v[90:91]
	v_add_u32_e32 v90, 64, v92
	global_load_dwordx4 v[184:187], v90, s[72:73]
	s_nop 0
	global_load_dwordx4 v[188:191], v[16:17], off offset:64
	global_load_dwordx4 v[192:195], v[16:17], off
	global_load_dwordx4 v[94:97], v0, s[72:73]
	global_load_dwordx4 v[98:101], v0, s[72:73] offset:64
	s_branch .LBB0_1326

.LBB0_1326:
	s_add_i32 s44, s36, -2
	s_cmpk_lt_u32 s44, 0x400
	s_cselect_b64 s[8:9], -1, 0
	s_cmpk_gt_u32 s44, 0x3ff
	s_cbranch_scc1 .LBB0_1328
	s_add_i32 s10, s40, 16
	s_add_i32 s11, s41, -16
	s_and_b64 s[6:7], s[0:1], exec
	s_cselect_b32 s6, s10, s11
	s_mul_i32 s7, s6, 0xe00
	s_cmp_eq_u32 s6, 0
	v_add_lshl_u32 v0, s7, v142, 1
	s_cselect_b32 s7, 0, 0xffffe400
	s_cmpk_lt_u32 s6, 0x3fff
	s_cselect_b32 s6, 0x1c00, 0
	v_add_u32_e32 v2, s7, v0
	v_add_u32_e32 v3, s6, v0
	v_add_u32_e32 v4, 0xfffff800, v0
	v_add_u32_e32 v5, 0x800, v0
	v_add_u32_e32 v102, 0xfffff800, v2
	v_add_u32_e32 v103, 0x800, v2
	v_add_u32_e32 v104, 0xfffff800, v3
	global_load_ushort v196, v4, s[72:73]
	s_nop 0
	global_load_ushort v197, v0, s[72:73]
	s_nop 0
	global_load_ushort v198, v5, s[72:73]
	s_nop 0
	global_load_ushort v199, v102, s[72:73]
	s_nop 0
	global_load_ushort v200, v2, s[72:73]
	s_nop 0
	global_load_ushort v201, v103, s[72:73]
	s_nop 0
	global_load_ushort v202, v104, s[72:73]
	s_nop 0
	global_load_ushort v203, v3, s[72:73]
	v_add_u32_e32 v2, 0x800, v3
	global_load_ushort v204, v2, s[72:73]
.LBB0_1328:
	v_cndmask_b32_e64 v0, 0, 1, s[8:9]
	v_cmp_ne_u32_e64 s[6:7], 1, v0
	s_andn2_b64 vcc, exec, s[8:9]
	s_cbranch_vccnz .LBB0_1330
	v_add3_u32 v0, v128, s40, 16
	v_add3_u32 v102, v147, s41, -16
	v_cndmask_b32_e64 v0, v102, v0, s[0:1]
	v_cmp_gt_u32_e32 vcc, s18, v0
	v_lshlrev_b32_e32 v103, 16, v70
	v_lshlrev_b32_e32 v102, 16, v66
	v_cndmask_b32_e64 v151, 0, 1.0, vcc
	v_cmp_eq_u32_e32 vcc, 0, v0
	v_lshlrev_b32_e32 v104, 16, v74
	v_and_b32_e32 v105, 0xffff0000, v74
	v_cndmask_b32_e64 v150, 1.0, 0, vcc
	v_pk_mul_f32 v[102:103], v[150:151], v[102:103]
	v_lshlrev_b32_e32 v152, 16, v75
	v_add_f32_e32 v0, v102, v103
	v_and_b32_e32 v103, 0xffff0000, v70
	v_and_b32_e32 v102, 0xffff0000, v66
	v_fma_f32 v0, v0, 0.5, -v104
	v_pk_mul_f32 v[102:103], v[150:151], v[102:103]
	v_fmac_f32_e32 v104, v50, v0
	v_add_f32_e32 v0, v102, v103
	v_lshlrev_b32_e32 v103, 16, v71
	v_lshlrev_b32_e32 v102, 16, v67
	v_fma_f32 v0, v0, 0.5, -v105
	v_pk_mul_f32 v[102:103], v[150:151], v[102:103]
	v_fmac_f32_e32 v105, v51, v0
	v_add_f32_e32 v0, v102, v103
	v_and_b32_e32 v103, 0xffff0000, v71
	v_and_b32_e32 v102, 0xffff0000, v67
	v_fma_f32 v0, v0, 0.5, -v152
	v_pk_mul_f32 v[102:103], v[150:151], v[102:103]
	v_and_b32_e32 v153, 0xffff0000, v75
	v_fmac_f32_e32 v152, v52, v0
	v_add_f32_e32 v0, v102, v103
	v_lshlrev_b32_e32 v103, 16, v72
	v_lshlrev_b32_e32 v102, 16, v68
	v_fma_f32 v0, v0, 0.5, -v153
	v_pk_mul_f32 v[102:103], v[150:151], v[102:103]
	v_lshlrev_b32_e32 v154, 16, v76
	v_fmac_f32_e32 v153, v53, v0
	v_add_f32_e32 v0, v102, v103
	v_and_b32_e32 v103, 0xffff0000, v72
	v_and_b32_e32 v102, 0xffff0000, v68
	v_fma_f32 v0, v0, 0.5, -v154
	v_pk_mul_f32 v[102:103], v[150:151], v[102:103]
	v_and_b32_e32 v155, 0xffff0000, v76
	v_fmac_f32_e32 v154, v54, v0
	v_add_f32_e32 v0, v102, v103
	v_lshlrev_b32_e32 v103, 16, v73
	v_lshlrev_b32_e32 v102, 16, v69
	v_fma_f32 v0, v0, 0.5, -v155
	v_pk_mul_f32 v[102:103], v[150:151], v[102:103]
	v_lshlrev_b32_e32 v156, 16, v77
	v_fmac_f32_e32 v155, v55, v0
	v_add_f32_e32 v0, v102, v103
	v_and_b32_e32 v103, 0xffff0000, v73
	v_and_b32_e32 v102, 0xffff0000, v69
	v_fma_f32 v0, v0, 0.5, -v156
	v_pk_mul_f32 v[102:103], v[150:151], v[102:103]
	v_fmac_f32_e32 v156, v56, v0
	v_add_f32_e32 v0, v102, v103
	v_add_f32_e32 v102, v104, v104
	v_mul_f32_e32 v102, 0x3fb8aa3b, v102
	v_add_f32_e32 v103, v105, v105
	v_exp_f32_e32 v102, v102
	v_mul_f32_e32 v103, 0x3fb8aa3b, v103
	v_exp_f32_e32 v103, v103
	v_and_b32_e32 v157, 0xffff0000, v77
	v_fma_f32 v0, v0, 0.5, -v157
	v_fmac_f32_e32 v157, v57, v0
	v_add_f32_e32 v0, 1.0, v102
	v_rcp_f32_e32 v102, v0
	v_add_f32_e32 v0, 1.0, v103
	v_add_f32_e32 v103, v152, v152
	v_mul_f32_e32 v103, 0x3fb8aa3b, v103
	v_exp_f32_e32 v104, v103
	v_add_f32_e32 v103, v153, v153
	v_mul_f32_e32 v103, 0x3fb8aa3b, v103
	v_exp_f32_e32 v105, v103
	v_rcp_f32_e32 v103, v0
	v_add_f32_e32 v0, 1.0, v104
	v_rcp_f32_e32 v104, v0
	v_add_f32_e32 v0, 1.0, v105
	v_add_f32_e32 v105, v154, v154
	v_mul_f32_e32 v105, 0x3fb8aa3b, v105
	v_exp_f32_e32 v152, v105
	v_add_f32_e32 v105, v155, v155
	v_mul_f32_e32 v105, 0x3fb8aa3b, v105
	v_exp_f32_e32 v153, v105
	v_rcp_f32_e32 v105, v0
	v_add_f32_e32 v0, 1.0, v152
	v_rcp_f32_e32 v152, v0
	v_add_f32_e32 v0, 1.0, v153
	v_add_f32_e32 v153, v156, v156
	v_mul_f32_e32 v153, 0x3fb8aa3b, v153
	v_exp_f32_e32 v154, v153
	v_add_f32_e32 v153, v157, v157
	v_mul_f32_e32 v153, 0x3fb8aa3b, v153
	v_exp_f32_e32 v155, v153
	v_rcp_f32_e32 v153, v0
	v_pk_fma_f32 v[102:103], v[102:103], 2.0, 1.0 op_sel_hi:[1,0,0] neg_lo:[1,0,0] neg_hi:[1,0,0]
	v_pk_fma_f32 v[104:105], v[104:105], 2.0, 1.0 op_sel_hi:[1,0,0] neg_lo:[1,0,0] neg_hi:[1,0,0]
	v_add_f32_e32 v0, 1.0, v154
	v_pk_fma_f32 v[152:153], v[152:153], 2.0, 1.0 op_sel_hi:[1,0,0] neg_lo:[1,0,0] neg_hi:[1,0,0]
	v_cvt_pk_bf16_f32 v102, v102, v103
	v_cvt_pk_bf16_f32 v103, v104, v105
	v_cvt_pk_bf16_f32 v104, v152, v153
	v_lshlrev_b32_e32 v153, 16, v86
	v_lshlrev_b32_e32 v152, 16, v82
	v_rcp_f32_e32 v154, v0
	v_add_f32_e32 v0, 1.0, v155
	v_pk_mul_f32 v[152:153], v[150:151], v[152:153]
	v_lshlrev_b32_e32 v158, 16, v78
	v_rcp_f32_e32 v155, v0
	v_add_f32_e32 v0, v152, v153
	v_and_b32_e32 v153, 0xffff0000, v86
	v_and_b32_e32 v152, 0xffff0000, v82
	v_fma_f32 v0, v0, 0.5, -v158
	v_pk_mul_f32 v[152:153], v[150:151], v[152:153]
	v_and_b32_e32 v159, 0xffff0000, v78
	v_fmac_f32_e32 v158, v58, v0
	v_add_f32_e32 v0, v152, v153
	v_lshlrev_b32_e32 v153, 16, v87
	v_lshlrev_b32_e32 v152, 16, v83
	v_fma_f32 v0, v0, 0.5, -v159
	v_pk_mul_f32 v[152:153], v[150:151], v[152:153]
	v_lshlrev_b32_e32 v160, 16, v79
	v_fmac_f32_e32 v159, v59, v0
	v_add_f32_e32 v0, v152, v153
	v_and_b32_e32 v153, 0xffff0000, v87
	v_and_b32_e32 v152, 0xffff0000, v83
	v_fma_f32 v0, v0, 0.5, -v160
	v_pk_mul_f32 v[152:153], v[150:151], v[152:153]
	v_and_b32_e32 v161, 0xffff0000, v79
	v_fmac_f32_e32 v160, v60, v0
	v_add_f32_e32 v0, v152, v153
	v_lshlrev_b32_e32 v153, 16, v88
	v_lshlrev_b32_e32 v152, 16, v84
	v_fma_f32 v0, v0, 0.5, -v161
	v_pk_mul_f32 v[152:153], v[150:151], v[152:153]
	v_lshlrev_b32_e32 v162, 16, v80
	v_fmac_f32_e32 v161, v61, v0
	v_add_f32_e32 v0, v152, v153
	v_and_b32_e32 v153, 0xffff0000, v88
	v_and_b32_e32 v152, 0xffff0000, v84
	v_fma_f32 v0, v0, 0.5, -v162
	v_pk_mul_f32 v[152:153], v[150:151], v[152:153]
	v_and_b32_e32 v163, 0xffff0000, v80
	v_fmac_f32_e32 v162, v62, v0
	v_add_f32_e32 v0, v152, v153
	v_lshlrev_b32_e32 v153, 16, v89
	v_lshlrev_b32_e32 v152, 16, v85
	v_fma_f32 v0, v0, 0.5, -v163
	v_pk_mul_f32 v[152:153], v[150:151], v[152:153]
	v_lshlrev_b32_e32 v164, 16, v81
	v_fmac_f32_e32 v163, v63, v0
	v_add_f32_e32 v0, v152, v153
	v_and_b32_e32 v153, 0xffff0000, v89
	v_and_b32_e32 v152, 0xffff0000, v85
	v_fma_f32 v0, v0, 0.5, -v164
	v_pk_mul_f32 v[150:151], v[150:151], v[152:153]
	v_fmac_f32_e32 v164, v64, v0
	v_add_f32_e32 v0, v150, v151
	v_add_f32_e32 v150, v158, v158
	v_mul_f32_e32 v150, 0x3fb8aa3b, v150
	v_add_f32_e32 v151, v159, v159
	v_exp_f32_e32 v150, v150
	v_mul_f32_e32 v151, 0x3fb8aa3b, v151
	v_exp_f32_e32 v151, v151
	v_and_b32_e32 v165, 0xffff0000, v81
	v_fma_f32 v0, v0, 0.5, -v165
	v_fmac_f32_e32 v165, v65, v0
	v_add_f32_e32 v0, 1.0, v150
	v_rcp_f32_e32 v150, v0
	v_add_f32_e32 v0, 1.0, v151
	v_add_f32_e32 v151, v160, v160
	v_mul_f32_e32 v151, 0x3fb8aa3b, v151
	v_exp_f32_e32 v152, v151
	v_add_f32_e32 v151, v161, v161
	v_mul_f32_e32 v151, 0x3fb8aa3b, v151
	v_exp_f32_e32 v153, v151
	v_rcp_f32_e32 v151, v0
	v_add_f32_e32 v0, 1.0, v152
	v_rcp_f32_e32 v152, v0
	v_add_f32_e32 v0, 1.0, v153
	v_add_f32_e32 v153, v162, v162
	v_pk_fma_f32 v[154:155], v[154:155], 2.0, 1.0 op_sel_hi:[1,0,0] neg_lo:[1,0,0] neg_hi:[1,0,0]
	v_mul_f32_e32 v153, 0x3fb8aa3b, v153
	v_cvt_pk_bf16_f32 v105, v154, v155
	v_exp_f32_e32 v154, v153
	v_add_f32_e32 v153, v163, v163
	v_mul_f32_e32 v153, 0x3fb8aa3b, v153
	v_exp_f32_e32 v155, v153
	v_rcp_f32_e32 v153, v0
	v_add_f32_e32 v0, 1.0, v154
	v_rcp_f32_e32 v154, v0
	v_add_f32_e32 v0, 1.0, v155
	v_add_f32_e32 v155, v164, v164
	v_mul_f32_e32 v155, 0x3fb8aa3b, v155
	v_exp_f32_e32 v156, v155
	v_add_f32_e32 v155, v165, v165
	v_mul_f32_e32 v155, 0x3fb8aa3b, v155
	v_exp_f32_e32 v157, v155
	v_rcp_f32_e32 v155, v0
	v_add_f32_e32 v0, 1.0, v156
	v_rcp_f32_e32 v156, v0
	v_add_f32_e32 v0, 1.0, v157
	v_rcp_f32_e32 v157, v0
	v_pk_fma_f32 v[150:151], v[150:151], 2.0, 1.0 op_sel_hi:[1,0,0] neg_lo:[1,0,0] neg_hi:[1,0,0]
	v_pk_fma_f32 v[152:153], v[152:153], 2.0, 1.0 op_sel_hi:[1,0,0] neg_lo:[1,0,0] neg_hi:[1,0,0]
	v_pk_fma_f32 v[154:155], v[154:155], 2.0, 1.0 op_sel_hi:[1,0,0] neg_lo:[1,0,0] neg_hi:[1,0,0]
	v_pk_fma_f32 v[158:159], v[156:157], 2.0, 1.0 op_sel_hi:[1,0,0] neg_lo:[1,0,0] neg_hi:[1,0,0]
	v_cvt_pk_bf16_f32 v150, v150, v151
	v_cvt_pk_bf16_f32 v151, v152, v153
	v_cvt_pk_bf16_f32 v152, v154, v155
	v_cvt_pk_bf16_f32 v153, v158, v159
	v_mfma_f32_16x16x32_bf16 v[154:157], v[102:105], v[18:21], 0
	s_add_i32 s8, s19, 1
	s_cmp_lg_u32 s19, 2
	v_mfma_f32_16x16x32_bf16 v[154:157], v[150:153], v[22:25], v[154:157]
	s_nop 7
	v_add_f32_e32 v0, v129, v154
	v_add_f32_e32 v154, v129, v155
	v_mul_f32_e32 v154, 0xbfb8aa3b, v154
	v_exp_f32_e32 v154, v154
	v_lshl_or_b32 v155, s19, 12, v143
	v_add_u32_e32 v158, v144, v155
	v_add_f32_e32 v155, v129, v156
	v_add_f32_e32 v154, 1.0, v154
	v_rcp_f32_e32 v154, v154
	v_mul_f32_e32 v155, 0xbfb8aa3b, v155
	v_exp_f32_e32 v155, v155
	v_mul_f32_e32 v0, 0xbfb8aa3b, v0
	v_mul_f32_e32 v154, 0xbf1b4598, v154
	v_mul_f32_e32 v154, 0x3fb8aa3b, v154
	v_exp_f32_e32 v159, v154
	v_add_f32_e32 v154, 1.0, v155
	v_rcp_f32_e32 v154, v154
	v_add_f32_e32 v155, v129, v157
	v_mul_f32_e32 v155, 0xbfb8aa3b, v155
	v_exp_f32_e32 v160, v155
	v_mul_f32_e32 v161, 0xbf1b4598, v154
	v_mfma_f32_16x16x32_bf16 v[154:157], v[102:105], v[26:29], 0
	v_exp_f32_e32 v0, v0
	v_add_f32_e32 v160, 1.0, v160
	v_rcp_f32_e32 v160, v160
	v_mfma_f32_16x16x32_bf16 v[154:157], v[150:153], v[30:33], v[154:157]
	v_add_f32_e32 v0, 1.0, v0
	v_rcp_f32_e32 v0, v0
	v_mul_f32_e32 v161, 0x3fb8aa3b, v161
	v_mul_f32_e32 v160, 0xbf1b4598, v160
	v_exp_f32_e32 v161, v161
	s_nop 2
	v_add_f32_e32 v154, v130, v154
	v_mul_f32_e32 v154, 0xbfb8aa3b, v154
	v_add_f32_e32 v155, v130, v155
	v_exp_f32_e32 v154, v154
	v_mul_f32_e32 v155, 0xbfb8aa3b, v155
	v_exp_f32_e32 v155, v155
	v_add_f32_e32 v156, v130, v156
	v_add_f32_e32 v154, 1.0, v154
	v_rcp_f32_e32 v154, v154
	v_add_f32_e32 v155, 1.0, v155
	v_rcp_f32_e32 v155, v155
	v_mul_f32_e32 v156, 0xbfb8aa3b, v156
	v_exp_f32_e32 v156, v156
	v_mul_f32_e32 v0, 0xbf1b4598, v0
	v_mul_f32_e32 v154, 0xbf1b4598, v154
	v_mul_f32_e32 v0, 0x3fb8aa3b, v0
	v_mul_f32_e32 v154, 0x3fb8aa3b, v154
	v_mul_f32_e32 v155, 0xbf1b4598, v155
	v_exp_f32_e32 v0, v0
	v_exp_f32_e32 v154, v154
	v_mul_f32_e32 v155, 0x3fb8aa3b, v155
	v_exp_f32_e32 v155, v155
	v_add_f32_e32 v156, 1.0, v156
	v_rcp_f32_e32 v156, v156
	ds_write2_b32 v158, v0, v154 offset1:16
	ds_write2_b32 v158, v159, v155 offset0:64 offset1:80
	v_add_f32_e32 v154, v130, v157
	v_mul_f32_e32 v154, 0xbfb8aa3b, v154
	v_mul_f32_e32 v0, 0xbf1b4598, v156
	v_exp_f32_e32 v159, v154
	v_mfma_f32_16x16x32_bf16 v[154:157], v[102:105], v[34:37], 0
	v_mul_f32_e32 v0, 0x3fb8aa3b, v0
	v_mul_f32_e32 v160, 0x3fb8aa3b, v160
	v_add_f32_e32 v159, 1.0, v159
	v_mfma_f32_16x16x32_bf16 v[154:157], v[150:153], v[38:41], v[154:157]
	v_rcp_f32_e32 v159, v159
	v_exp_f32_e32 v0, v0
	v_exp_f32_e32 v160, v160
	v_mfma_f32_16x16x32_bf16 v[102:105], v[102:105], v[42:45], 0
	v_mul_f32_e32 v159, 0xbf1b4598, v159
	s_nop 2
	v_add_f32_e32 v154, v131, v154
	v_mul_f32_e32 v154, 0xbfb8aa3b, v154
	v_exp_f32_e32 v154, v154
	v_add_f32_e32 v155, v131, v155
	v_mfma_f32_16x16x32_bf16 v[102:105], v[150:153], v[46:49], v[102:105]
	v_mul_f32_e32 v155, 0xbfb8aa3b, v155
	v_add_f32_e32 v154, 1.0, v154
	v_mul_f32_e32 v159, 0x3fb8aa3b, v159
	v_rcp_f32_e32 v154, v154
	v_exp_f32_e32 v155, v155
	v_exp_f32_e32 v159, v159
	s_nop 1
	v_add_f32_e32 v102, v132, v102
	v_mul_f32_e32 v102, 0xbfb8aa3b, v102
	v_add_f32_e32 v103, v132, v103
	ds_write2_b32 v158, v161, v0 offset0:128 offset1:144
	ds_write2_b32 v158, v160, v159 offset0:192 offset1:208
	v_mul_f32_e32 v0, 0xbf1b4598, v154
	v_add_f32_e32 v154, 1.0, v155
	v_add_f32_e32 v155, v131, v156
	v_exp_f32_e32 v102, v102
	v_mul_f32_e32 v103, 0xbfb8aa3b, v103
	v_add_f32_e32 v104, v132, v104
	v_mul_f32_e32 v155, 0xbfb8aa3b, v155
	v_add_f32_e32 v156, v131, v157
	v_exp_f32_e32 v103, v103
	v_mul_f32_e32 v104, 0xbfb8aa3b, v104
	v_add_f32_e32 v105, v132, v105
	v_exp_f32_e32 v155, v155
	v_mul_f32_e32 v156, 0xbfb8aa3b, v156
	v_exp_f32_e32 v104, v104
	v_mul_f32_e32 v105, 0xbfb8aa3b, v105
	v_exp_f32_e32 v156, v156
	v_exp_f32_e32 v105, v105
	v_add_f32_e32 v102, 1.0, v102
	v_rcp_f32_e32 v102, v102
	v_add_f32_e32 v103, 1.0, v103
	v_rcp_f32_e32 v154, v154
	v_add_f32_e32 v155, 1.0, v155
	v_rcp_f32_e32 v103, v103
	v_add_f32_e32 v104, 1.0, v104
	v_rcp_f32_e32 v155, v155
	v_add_f32_e32 v156, 1.0, v156
	v_rcp_f32_e32 v104, v104
	v_add_f32_e32 v105, 1.0, v105
	v_rcp_f32_e32 v156, v156
	v_rcp_f32_e32 v105, v105
	v_mul_f32_e32 v102, 0xbf1b4598, v102
	v_mul_f32_e32 v0, 0x3fb8aa3b, v0
	v_mul_f32_e32 v154, 0xbf1b4598, v154
	v_mul_f32_e32 v102, 0x3fb8aa3b, v102
	v_mul_f32_e32 v103, 0xbf1b4598, v103
	v_exp_f32_e32 v0, v0
	v_mul_f32_e32 v154, 0x3fb8aa3b, v154
	v_mul_f32_e32 v155, 0xbf1b4598, v155
	v_exp_f32_e32 v102, v102
	v_mul_f32_e32 v103, 0x3fb8aa3b, v103
	v_mul_f32_e32 v104, 0xbf1b4598, v104
	v_exp_f32_e32 v154, v154
	v_mul_f32_e32 v155, 0x3fb8aa3b, v155
	v_mul_f32_e32 v156, 0xbf1b4598, v156
	v_exp_f32_e32 v103, v103
	v_mul_f32_e32 v104, 0x3fb8aa3b, v104
	v_mul_f32_e32 v105, 0xbf1b4598, v105
	v_exp_f32_e32 v155, v155
	v_mul_f32_e32 v156, 0x3fb8aa3b, v156
	v_exp_f32_e32 v104, v104
	v_mul_f32_e32 v105, 0x3fb8aa3b, v105
	v_exp_f32_e32 v150, v156
	v_exp_f32_e32 v105, v105
	s_cselect_b32 s19, s8, 0
	ds_write2_b32 v158, v0, v102 offset0:32 offset1:48
	ds_write2_b32 v158, v154, v103 offset0:96 offset1:112
	ds_write2_b32 v158, v155, v104 offset0:160 offset1:176
	ds_write2_b32 v158, v150, v105 offset0:224 offset1:240
.LBB0_1330:
	s_waitcnt vmcnt(0)
	s_add_i32 vcc_lo, s36, -1
	s_cmpk_gt_u32 vcc_lo, 0x3ff
	s_cbranch_scc1 .Lmy_w4_skA
	v_mov_b32_e32 v120, v183
	v_mov_b32_e32 v122, v182
	v_mov_b32_e32 v124, v181
	v_mov_b32_e32 v126, v180
	v_mov_b32_e32 v16, v183
	v_mov_b32_e32 v106, v181
	v_mov_b32_e32 v112, v187
	v_mov_b32_e32 v113, v191
	v_mov_b32_e32 v114, v186
	v_mov_b32_e32 v115, v190
	v_mov_b32_e32 v116, v185
	v_mov_b32_e32 v117, v189
	v_mov_b32_e32 v118, v184
	v_mov_b32_e32 v119, v188
	v_mov_b32_e32 v121, v195
	v_mov_b32_e32 v123, v194
	v_mov_b32_e32 v125, v193
	v_mov_b32_e32 v127, v192
	v_mov_b32_e32 v108, v187
	v_mov_b32_e32 v109, v191
	v_mov_b32_e32 v93, v190
	v_mov_b32_e32 v110, v185
	v_mov_b32_e32 v111, v189
	v_mov_b32_e32 v91, v188
	v_mov_b32_e32 v17, v195
	v_mov_b32_e32 v15, v194
	v_mov_b32_e32 v107, v193
	v_mov_b32_e32 v13, v192
	v_mov_b32_e32 v12, v180
	v_mov_b32_e32 v14, v182
	v_mov_b32_e32 v90, v184
	v_mov_b32_e32 v92, v186
.Lmy_w4_skA:
	s_add_i32 vcc_lo, s36, -2
	s_cmpk_gt_u32 vcc_lo, 0x3ff
	s_cbranch_scc1 .Lmy_w4_skR
	v_perm_b32 v2, v197, v196, s42
	v_perm_b32 v4, v201, v200, s42
	v_perm_b32 v5, v203, v202, s42
	v_bfi_b32 v6, s43, v204, v6
	v_perm_b32 v3, v199, v198, s42
.Lmy_w4_skR:
	s_add_i32 s8, s36, -4
	v_cndmask_b32_e64 v0, 0, 1, s[14:15]
	s_cmp_lt_i32 s8, 0
	v_cmp_ne_u32_e64 s[8:9], 1, v0
	s_cbranch_scc1 .LBB0_1335
	s_and_b64 s[10:11], s[0:1], exec
	s_cselect_b32 s45, s40, s41
	s_cmpk_lt_u32 s45, 0x3fff
	s_cselect_b64 s[10:11], -1, 0
	v_cndmask_b32_e64 v102, 0, 1.0, s[10:11]
	v_lshlrev_b32_e32 v103, 16, v8
	v_and_b32_e32 v104, 0xffff0000, v9
	v_and_b32_e32 v0, 0xffff0000, v6
	v_fmac_f32_e32 v103, v102, v104
	v_fma_f32 v103, v103, 0.5, -v0
	v_and_b32_e32 v104, 0xffff0000, v8
	v_lshlrev_b32_e32 v105, 16, v10
	v_fmac_f32_e32 v0, v137, v103
	v_lshlrev_b32_e32 v103, 16, v7
	v_fmac_f32_e32 v104, v102, v105
	v_fma_f32 v104, v104, 0.5, -v103
	v_lshlrev_b32_e32 v105, 16, v9
	v_and_b32_e32 v150, 0xffff0000, v10
	v_fmac_f32_e32 v103, v138, v104
	v_and_b32_e32 v104, 0xffff0000, v7
	v_fmac_f32_e32 v105, v102, v150
	v_fma_f32 v102, v105, 0.5, -v104
	v_mul_f32_e32 v105, v134, v103
	v_fmac_f32_e32 v104, v139, v102
	v_mul_f32_e32 v102, v105, v105
	v_mov_b32_e32 v151, 0
	ds_read_b32 v150, v145 offset:16384
	v_mov_b32_dpp v102, v102 quad_perm:[1,0,3,2] row_mask:0xf bank_mask:0xf bound_ctrl:1
	v_fmac_f32_e32 v102, v105, v105
	s_and_b64 vcc, exec, s[8:9]
	s_nop 0
	v_add_f32_dpp v102, v102, v102 quad_perm:[2,3,0,1] row_mask:0xf bank_mask:0xf bound_ctrl:1
	s_nop 1
	v_add_f32_dpp v102, v102, v102 row_half_mirror row_mask:0xf bank_mask:0xf bound_ctrl:1
	s_nop 1
	v_add_f32_dpp v102, v102, v102 row_mirror row_mask:0xf bank_mask:0xf bound_ctrl:1
	s_nop 1
	v_mov_b32_dpp v151, v102 row_bcast:15 row_mask:0xa bank_mask:0xf
	v_add_f32_e32 v102, v102, v151
	v_mov_b32_e32 v151, 0
	s_nop 1
	v_mov_b32_dpp v151, v102 row_bcast:31 row_mask:0xc bank_mask:0xf
	v_add_f32_e32 v102, v102, v151
	s_nop 0
	v_readlane_b32 s10, v102, 63
	s_nop 1
	v_max_f32_e64 v102, s10, s10
	v_max_f32_e32 v102, 0x179abe15, v102
	v_rsq_f32_e32 v151, v102
	s_waitcnt lgkmcnt(0)
	v_add_f32_e32 v102, -1.0, v150
	v_fma_f32 v102, v135, v102, 1.0
	v_mul_f32_e32 v102, v103, v102
	v_mul_f32_e32 v103, v105, v151
	v_mul_f32_e32 v105, v150, v103
	ds_write2st64_b32 v145, v103, v105 offset0:160 offset1:161
	ds_write2st64_b32 v145, v102, v0 offset0:162 offset1:163
	ds_write_b32 v145, v104 offset:41984
	s_cbranch_vccnz .LBB0_1335
	v_mul_f32_e32 v0, v0, v102
	v_mul_f32_e32 v102, v136, v0
	s_nop 1
	v_mov_b32_dpp v102, v102 quad_perm:[1,0,3,2] row_mask:0xf bank_mask:0xf bound_ctrl:1
	v_fmac_f32_e32 v102, v136, v0
	s_nop 1
	v_add_f32_dpp v0, v102, v102 quad_perm:[2,3,0,1] row_mask:0xf bank_mask:0xf bound_ctrl:1
	v_mov_b32_e32 v102, 0
	s_nop 0
	v_add_f32_dpp v0, v0, v0 row_half_mirror row_mask:0xf bank_mask:0xf bound_ctrl:1
	s_nop 1
	v_add_f32_dpp v0, v0, v0 row_mirror row_mask:0xf bank_mask:0xf bound_ctrl:1
	s_nop 1
	v_mov_b32_dpp v102, v0 row_bcast:15 row_mask:0xa bank_mask:0xf
	v_add_f32_e32 v0, v0, v102
	v_mov_b32_e32 v102, 0
	s_nop 1
	v_mov_b32_dpp v102, v0 row_bcast:31 row_mask:0xc bank_mask:0xf
	v_add_f32_e32 v0, v0, v102
	s_nop 0
	v_readlane_b32 s48, v0, 63
	s_and_saveexec_b64 s[10:11], s[4:5]
	s_cbranch_execz .LBB0_1334
	s_lshl_b32 s45, s45, 7
	s_add_i32 s45, s45, s60
	v_mov_b32_e32 v0, s45
	v_mov_b32_e32 v102, s48
	global_store_dword v0, v102, s[24:25]

.LBB0_1335:
	s_waitcnt lgkmcnt(0)
	s_barrier
	s_cmpk_gt_u32 s36, 0x3ff
	s_cbranch_scc1 .LBB0_1337
	v_add3_u32 v0, v128, s40, 48
	v_subrev_u32_e32 v66, 48, v149
	v_cndmask_b32_e64 v68, v66, v0, s[0:1]
	v_mul_lo_u32 v0, v68, s37
	v_cmp_eq_u32_e32 vcc, 0, v68
	v_add_lshl_u32 v0, v0, v133, 1
	v_mov_b32_e32 v69, v1
	v_cndmask_b32_e64 v66, v140, 0, vcc
	v_cmp_gt_u32_e32 vcc, s18, v68
	v_add_u32_e32 v82, v0, v66
	v_lshl_add_u64 v[66:67], s[72:73], 0, v[0:1]
	v_cndmask_b32_e32 v68, 0, v141, vcc
	v_lshl_add_u64 v[86:87], v[66:67], 0, v[68:69]
	global_load_dwordx4 v[66:69], v82, s[72:73]
	global_load_dwordx4 v[70:73], v[86:87], off
	global_load_dwordx4 v[74:77], v0, s[72:73]
	global_load_dwordx4 v[78:81], v0, s[72:73] offset:64
	v_add_u32_e32 v0, 64, v82
	global_load_dwordx4 v[82:85], v0, s[72:73]
	s_nop 0
	global_load_dwordx4 v[86:89], v[86:87], off offset:64
.LBB0_1337:
	v_cndmask_b32_e64 v0, 0, 1, s[16:17]
	v_cmp_ne_u32_e64 s[10:11], 1, v0
	s_andn2_b64 vcc, exec, s[16:17]
	s_cbranch_vccnz .LBB0_1339
	s_add_i32 s45, s40, 32
	s_sub_i32 s48, s41, 32
	s_and_b64 s[16:17], s[0:1], exec
	s_cselect_b32 s16, s45, s48
	s_mulk_i32 s16, 0xe00
	v_add_lshl_u32 v0, s16, v142, 1
	v_add_u32_e32 v8, 0x1c00, v0
	v_add_u32_e32 v9, 0x800, v0
	v_add_u32_e32 v10, 0xffffdc00, v0
	v_add_u32_e32 v102, 0xffffec00, v0
	v_add_u32_e32 v103, 0x1400, v0
	v_add_u32_e32 v7, 0xffffe400, v0
	global_load_ushort v196, v9, s[72:73]
	global_load_ushort v197, v10, s[72:73]
	s_nop 0
	global_load_ushort v198, v102, s[72:73]
	s_nop 0
	global_load_ushort v199, v103, s[72:73]
	s_nop 0
	global_load_ushort v200, v8, s[72:73]
	v_add_u32_e32 v10, 0x2400, v0
	v_add_u32_e32 v103, 0xfffff800, v0
	global_load_ushort v201, v10, s[72:73]
	s_nop 0
	global_load_ushort v202, v7, s[72:73]
	s_nop 0
	global_load_ushort v203, v0, s[72:73]
	s_nop 0
	global_load_ushort v204, v103, s[72:73]
.LBB0_1339:
	s_and_b64 vcc, exec, s[10:11]
	s_cbranch_vccnz .LBB0_1341
	v_cndmask_b32_e64 v0, v148, v11, s[0:1]
	v_cmp_gt_u32_e32 vcc, s18, v0
	v_and_b32_e32 v103, 0xffff0000, v127
	v_and_b32_e32 v102, 0xffff0000, v126
	v_cndmask_b32_e64 v161, 0, 1.0, vcc
	v_cmp_eq_u32_e32 vcc, 0, v0
	v_lshlrev_b32_e32 v127, 16, v127
	v_lshlrev_b32_e32 v126, 16, v126
	v_cndmask_b32_e64 v160, 1.0, 0, vcc
	v_pk_mul_f32 v[126:127], v[160:161], v[126:127]
	v_lshlrev_b32_e32 v11, 16, v94
	v_add_f32_e32 v0, v126, v127
	v_fma_f32 v0, v0, 0.5, -v11
	v_pk_mul_f32 v[102:103], v[160:161], v[102:103]
	v_and_b32_e32 v162, 0xffff0000, v94
	v_fmac_f32_e32 v11, v50, v0
	v_add_f32_e32 v0, v102, v103
	v_lshlrev_b32_e32 v103, 16, v125
	v_lshlrev_b32_e32 v102, 16, v124
	v_fma_f32 v0, v0, 0.5, -v162
	v_pk_mul_f32 v[102:103], v[160:161], v[102:103]
	v_lshlrev_b32_e32 v163, 16, v95
	v_and_b32_e32 v105, 0xffff0000, v125
	v_and_b32_e32 v104, 0xffff0000, v124
	v_fmac_f32_e32 v162, v51, v0
	v_add_f32_e32 v0, v102, v103
	v_fma_f32 v0, v0, 0.5, -v163
	v_pk_mul_f32 v[102:103], v[160:161], v[104:105]
	v_and_b32_e32 v164, 0xffff0000, v95
	v_fmac_f32_e32 v163, v52, v0
	v_add_f32_e32 v0, v102, v103
	v_lshlrev_b32_e32 v103, 16, v123
	v_lshlrev_b32_e32 v102, 16, v122
	v_fma_f32 v0, v0, 0.5, -v164
	v_pk_mul_f32 v[102:103], v[160:161], v[102:103]
	v_lshlrev_b32_e32 v165, 16, v96
	v_and_b32_e32 v149, 0xffff0000, v123
	v_and_b32_e32 v148, 0xffff0000, v122
	v_fmac_f32_e32 v164, v53, v0
	v_add_f32_e32 v0, v102, v103
	v_fma_f32 v0, v0, 0.5, -v165
	v_pk_mul_f32 v[102:103], v[160:161], v[148:149]
	v_and_b32_e32 v166, 0xffff0000, v96
	v_fmac_f32_e32 v165, v54, v0
	v_add_f32_e32 v0, v102, v103
	v_lshlrev_b32_e32 v103, 16, v121
	v_lshlrev_b32_e32 v102, 16, v120
	v_fma_f32 v0, v0, 0.5, -v166
	v_pk_mul_f32 v[102:103], v[160:161], v[102:103]
	v_lshlrev_b32_e32 v167, 16, v97
	v_and_b32_e32 v151, 0xffff0000, v121
	v_and_b32_e32 v150, 0xffff0000, v120
	v_fmac_f32_e32 v166, v55, v0
	v_add_f32_e32 v0, v102, v103
	v_fma_f32 v0, v0, 0.5, -v167
	v_pk_mul_f32 v[102:103], v[160:161], v[150:151]
	v_add_f32_e32 v11, v11, v11
	v_fmac_f32_e32 v167, v56, v0
	v_add_f32_e32 v0, v102, v103
	v_mul_f32_e32 v11, 0x3fb8aa3b, v11
	v_add_f32_e32 v102, v162, v162
	v_exp_f32_e32 v11, v11
	v_mul_f32_e32 v102, 0x3fb8aa3b, v102
	v_exp_f32_e32 v103, v102
	v_and_b32_e32 v168, 0xffff0000, v97
	v_fma_f32 v0, v0, 0.5, -v168
	v_fmac_f32_e32 v168, v57, v0
	v_add_f32_e32 v0, 1.0, v11
	v_add_f32_e32 v11, v163, v163
	v_rcp_f32_e32 v102, v0
	v_add_f32_e32 v0, 1.0, v103
	v_mul_f32_e32 v11, 0x3fb8aa3b, v11
	v_add_f32_e32 v103, v164, v164
	v_exp_f32_e32 v11, v11
	v_mul_f32_e32 v103, 0x3fb8aa3b, v103
	v_exp_f32_e32 v105, v103
	v_rcp_f32_e32 v103, v0
	v_add_f32_e32 v0, 1.0, v11
	v_add_f32_e32 v11, v165, v165
	v_rcp_f32_e32 v104, v0
	v_add_f32_e32 v0, 1.0, v105
	v_mul_f32_e32 v11, 0x3fb8aa3b, v11
	v_add_f32_e32 v105, v166, v166
	v_exp_f32_e32 v11, v11
	v_mul_f32_e32 v105, 0x3fb8aa3b, v105
	v_exp_f32_e32 v121, v105
	v_rcp_f32_e32 v105, v0
	v_add_f32_e32 v0, 1.0, v11
	v_add_f32_e32 v11, v167, v167
	v_rcp_f32_e32 v120, v0
	v_add_f32_e32 v0, 1.0, v121
	v_mul_f32_e32 v11, 0x3fb8aa3b, v11
	v_add_f32_e32 v121, v168, v168
	v_exp_f32_e32 v11, v11
	v_mul_f32_e32 v121, 0x3fb8aa3b, v121
	v_exp_f32_e32 v123, v121
	v_and_b32_e32 v153, 0xffff0000, v119
	v_and_b32_e32 v152, 0xffff0000, v118
	v_rcp_f32_e32 v121, v0
	v_add_f32_e32 v0, 1.0, v11
	v_lshlrev_b32_e32 v119, 16, v119
	v_lshlrev_b32_e32 v118, 16, v118
	v_rcp_f32_e32 v122, v0
	v_add_f32_e32 v0, 1.0, v123
	v_pk_mul_f32 v[118:119], v[160:161], v[118:119]
	v_lshlrev_b32_e32 v169, 16, v98
	v_rcp_f32_e32 v123, v0
	v_add_f32_e32 v0, v118, v119
	v_fma_f32 v0, v0, 0.5, -v169
	v_pk_mul_f32 v[118:119], v[160:161], v[152:153]
	v_and_b32_e32 v170, 0xffff0000, v98
	v_and_b32_e32 v155, 0xffff0000, v117
	v_and_b32_e32 v154, 0xffff0000, v116
	v_fmac_f32_e32 v169, v58, v0
	v_add_f32_e32 v0, v118, v119
	v_lshlrev_b32_e32 v117, 16, v117
	v_lshlrev_b32_e32 v116, 16, v116
	v_fma_f32 v0, v0, 0.5, -v170
	v_pk_mul_f32 v[116:117], v[160:161], v[116:117]
	v_lshlrev_b32_e32 v171, 16, v99
	v_fmac_f32_e32 v170, v59, v0
	v_add_f32_e32 v0, v116, v117
	v_fma_f32 v0, v0, 0.5, -v171
	v_pk_mul_f32 v[116:117], v[160:161], v[154:155]
	v_and_b32_e32 v172, 0xffff0000, v99
	v_and_b32_e32 v157, 0xffff0000, v115
	v_and_b32_e32 v156, 0xffff0000, v114
	v_fmac_f32_e32 v171, v60, v0
	v_add_f32_e32 v0, v116, v117
	v_lshlrev_b32_e32 v115, 16, v115
	v_lshlrev_b32_e32 v114, 16, v114
	v_fma_f32 v0, v0, 0.5, -v172
	v_pk_mul_f32 v[114:115], v[160:161], v[114:115]
	v_lshlrev_b32_e32 v173, 16, v100
	v_fmac_f32_e32 v172, v61, v0
	v_add_f32_e32 v0, v114, v115
	v_fma_f32 v0, v0, 0.5, -v173
	v_pk_mul_f32 v[114:115], v[160:161], v[156:157]
	v_and_b32_e32 v174, 0xffff0000, v100
	v_and_b32_e32 v159, 0xffff0000, v113
	v_and_b32_e32 v158, 0xffff0000, v112
	v_fmac_f32_e32 v173, v62, v0
	v_add_f32_e32 v0, v114, v115
	v_lshlrev_b32_e32 v113, 16, v113
	v_lshlrev_b32_e32 v112, 16, v112
	v_fma_f32 v0, v0, 0.5, -v174
	v_pk_mul_f32 v[112:113], v[160:161], v[112:113]
	v_lshlrev_b32_e32 v175, 16, v101
	v_fmac_f32_e32 v174, v63, v0
	v_add_f32_e32 v0, v112, v113
	v_fma_f32 v0, v0, 0.5, -v175
	v_pk_mul_f32 v[112:113], v[160:161], v[158:159]
	v_add_f32_e32 v11, v169, v169
	v_fmac_f32_e32 v175, v64, v0
	v_add_f32_e32 v0, v112, v113
	v_mul_f32_e32 v11, 0x3fb8aa3b, v11
	v_add_f32_e32 v112, v170, v170
	v_exp_f32_e32 v11, v11
	v_mul_f32_e32 v112, 0x3fb8aa3b, v112
	v_exp_f32_e32 v113, v112
	v_and_b32_e32 v176, 0xffff0000, v101
	v_fma_f32 v0, v0, 0.5, -v176
	v_fmac_f32_e32 v176, v65, v0
	v_add_f32_e32 v0, 1.0, v11
	v_add_f32_e32 v11, v171, v171
	v_rcp_f32_e32 v112, v0
	v_add_f32_e32 v0, 1.0, v113
	v_mul_f32_e32 v11, 0x3fb8aa3b, v11
	v_add_f32_e32 v113, v172, v172
	v_exp_f32_e32 v11, v11
	v_mul_f32_e32 v113, 0x3fb8aa3b, v113
	v_exp_f32_e32 v115, v113
	v_rcp_f32_e32 v113, v0
	v_add_f32_e32 v0, 1.0, v11
	v_add_f32_e32 v11, v173, v173
	v_rcp_f32_e32 v114, v0
	v_add_f32_e32 v0, 1.0, v115
	v_mul_f32_e32 v11, 0x3fb8aa3b, v11
	v_add_f32_e32 v115, v174, v174
	v_exp_f32_e32 v11, v11
	v_mul_f32_e32 v115, 0x3fb8aa3b, v115
	v_exp_f32_e32 v117, v115
	v_rcp_f32_e32 v115, v0
	v_add_f32_e32 v0, 1.0, v11
	v_add_f32_e32 v11, v175, v175
	v_rcp_f32_e32 v116, v0
	v_add_f32_e32 v0, 1.0, v117
	v_mul_f32_e32 v11, 0x3fb8aa3b, v11
	v_add_f32_e32 v117, v176, v176
	v_exp_f32_e32 v11, v11
	v_mul_f32_e32 v117, 0x3fb8aa3b, v117
	v_exp_f32_e32 v119, v117
	v_rcp_f32_e32 v117, v0
	v_add_f32_e32 v0, 1.0, v11
	v_rcp_f32_e32 v118, v0
	v_add_f32_e32 v0, 1.0, v119
	v_pk_fma_f32 v[102:103], v[102:103], 2.0, 1.0 op_sel_hi:[1,0,0] neg_lo:[1,0,0] neg_hi:[1,0,0]
	v_pk_fma_f32 v[104:105], v[104:105], 2.0, 1.0 op_sel_hi:[1,0,0] neg_lo:[1,0,0] neg_hi:[1,0,0]
	v_pk_fma_f32 v[120:121], v[120:121], 2.0, 1.0 op_sel_hi:[1,0,0] neg_lo:[1,0,0] neg_hi:[1,0,0]
	v_pk_fma_f32 v[122:123], v[122:123], 2.0, 1.0 op_sel_hi:[1,0,0] neg_lo:[1,0,0] neg_hi:[1,0,0]
	v_rcp_f32_e32 v119, v0
	v_cvt_pk_bf16_f32 v102, v102, v103
	v_cvt_pk_bf16_f32 v103, v104, v105
	v_cvt_pk_bf16_f32 v104, v120, v121
	v_cvt_pk_bf16_f32 v105, v122, v123
	v_pk_fma_f32 v[112:113], v[112:113], 2.0, 1.0 op_sel_hi:[1,0,0] neg_lo:[1,0,0] neg_hi:[1,0,0]
	v_pk_fma_f32 v[114:115], v[114:115], 2.0, 1.0 op_sel_hi:[1,0,0] neg_lo:[1,0,0] neg_hi:[1,0,0]
	v_pk_fma_f32 v[116:117], v[116:117], 2.0, 1.0 op_sel_hi:[1,0,0] neg_lo:[1,0,0] neg_hi:[1,0,0]
	v_pk_fma_f32 v[120:121], v[118:119], 2.0, 1.0 op_sel_hi:[1,0,0] neg_lo:[1,0,0] neg_hi:[1,0,0]
	v_cvt_pk_bf16_f32 v112, v112, v113
	v_cvt_pk_bf16_f32 v113, v114, v115
	v_cvt_pk_bf16_f32 v114, v116, v117
	v_cvt_pk_bf16_f32 v115, v120, v121
	v_mfma_f32_16x16x32_bf16 v[116:119], v[102:105], v[18:21], 0
	v_lshl_or_b32 v11, s19, 12, v143
	v_add_u32_e32 v11, v144, v11
	s_add_i32 s10, s19, 1
	v_mfma_f32_16x16x32_bf16 v[116:119], v[112:115], v[22:25], v[116:119]
	s_cmp_lg_u32 s19, 2
	s_cselect_b32 s19, s10, 0
	s_nop 5
	v_add_f32_e32 v0, v129, v116
	v_add_f32_e32 v116, v129, v117
	v_mul_f32_e32 v116, 0xbfb8aa3b, v116
	v_exp_f32_e32 v116, v116
	v_add_f32_e32 v117, v129, v118
	v_mul_f32_e32 v117, 0xbfb8aa3b, v117
	v_exp_f32_e32 v117, v117
	v_add_f32_e32 v116, 1.0, v116
	v_rcp_f32_e32 v116, v116
	v_mul_f32_e32 v0, 0xbfb8aa3b, v0
	v_exp_f32_e32 v0, v0
	v_mul_f32_e32 v116, 0xbf1b4598, v116
	v_mul_f32_e32 v116, 0x3fb8aa3b, v116
	v_exp_f32_e32 v120, v116
	v_add_f32_e32 v116, 1.0, v117
	v_rcp_f32_e32 v116, v116
	v_add_f32_e32 v117, v129, v119
	v_mul_f32_e32 v117, 0xbfb8aa3b, v117
	v_exp_f32_e32 v121, v117
	v_mul_f32_e32 v122, 0xbf1b4598, v116
	v_mfma_f32_16x16x32_bf16 v[116:119], v[102:105], v[26:29], 0
	v_add_f32_e32 v0, 1.0, v0
	v_rcp_f32_e32 v0, v0
	v_add_f32_e32 v121, 1.0, v121
	v_mfma_f32_16x16x32_bf16 v[116:119], v[112:115], v[30:33], v[116:119]
	v_rcp_f32_e32 v121, v121
	v_mul_f32_e32 v0, 0xbf1b4598, v0
	v_mul_f32_e32 v0, 0x3fb8aa3b, v0
	v_exp_f32_e32 v0, v0
	v_mul_f32_e32 v122, 0x3fb8aa3b, v122
	s_nop 2
	v_add_f32_e32 v116, v130, v116
	v_mul_f32_e32 v116, 0xbfb8aa3b, v116
	v_add_f32_e32 v117, v130, v117
	v_exp_f32_e32 v116, v116
	v_mul_f32_e32 v117, 0xbfb8aa3b, v117
	v_exp_f32_e32 v117, v117
	v_add_f32_e32 v118, v130, v118
	v_add_f32_e32 v116, 1.0, v116
	v_rcp_f32_e32 v116, v116
	v_add_f32_e32 v117, 1.0, v117
	v_rcp_f32_e32 v117, v117
	v_mul_f32_e32 v118, 0xbfb8aa3b, v118
	v_exp_f32_e32 v118, v118
	v_mul_f32_e32 v116, 0xbf1b4598, v116
	v_mul_f32_e32 v116, 0x3fb8aa3b, v116
	v_mul_f32_e32 v117, 0xbf1b4598, v117
	v_exp_f32_e32 v116, v116
	v_mul_f32_e32 v117, 0x3fb8aa3b, v117
	v_exp_f32_e32 v117, v117
	v_add_f32_e32 v118, 1.0, v118
	v_rcp_f32_e32 v118, v118
	ds_write2_b32 v11, v0, v116 offset1:16
	ds_write2_b32 v11, v120, v117 offset0:64 offset1:80
	v_add_f32_e32 v116, v130, v119
	v_mul_f32_e32 v116, 0xbfb8aa3b, v116
	v_mul_f32_e32 v0, 0xbf1b4598, v118
	v_exp_f32_e32 v120, v116
	v_mfma_f32_16x16x32_bf16 v[116:119], v[102:105], v[34:37], 0
	v_mul_f32_e32 v121, 0xbf1b4598, v121
	v_mul_f32_e32 v0, 0x3fb8aa3b, v0
	v_add_f32_e32 v120, 1.0, v120
	v_mfma_f32_16x16x32_bf16 v[116:119], v[112:115], v[38:41], v[116:119]
	v_rcp_f32_e32 v120, v120
	v_exp_f32_e32 v122, v122
	v_mul_f32_e32 v121, 0x3fb8aa3b, v121
	v_mfma_f32_16x16x32_bf16 v[102:105], v[102:105], v[42:45], 0
	v_mul_f32_e32 v120, 0xbf1b4598, v120
	s_nop 2
	v_add_f32_e32 v116, v131, v116
	v_mul_f32_e32 v116, 0xbfb8aa3b, v116
	v_exp_f32_e32 v116, v116
	v_add_f32_e32 v117, v131, v117
	v_mfma_f32_16x16x32_bf16 v[102:105], v[112:115], v[46:49], v[102:105]
	v_mul_f32_e32 v117, 0xbfb8aa3b, v117
	v_add_f32_e32 v116, 1.0, v116
	v_exp_f32_e32 v0, v0
	v_mul_f32_e32 v120, 0x3fb8aa3b, v120
	v_rcp_f32_e32 v116, v116
	v_exp_f32_e32 v117, v117
	v_exp_f32_e32 v121, v121
	v_exp_f32_e32 v120, v120
	v_add_f32_e32 v102, v132, v102
	v_mul_f32_e32 v102, 0xbfb8aa3b, v102
	v_add_f32_e32 v103, v132, v103
	ds_write2_b32 v11, v122, v0 offset0:128 offset1:144
	ds_write2_b32 v11, v121, v120 offset0:192 offset1:208
	v_mul_f32_e32 v0, 0xbf1b4598, v116
	v_add_f32_e32 v116, 1.0, v117
	v_add_f32_e32 v117, v131, v118
	v_exp_f32_e32 v102, v102
	v_mul_f32_e32 v103, 0xbfb8aa3b, v103
	v_add_f32_e32 v104, v132, v104
	v_mul_f32_e32 v117, 0xbfb8aa3b, v117
	v_add_f32_e32 v118, v131, v119
	v_exp_f32_e32 v103, v103
	v_mul_f32_e32 v104, 0xbfb8aa3b, v104
	v_add_f32_e32 v105, v132, v105
	v_exp_f32_e32 v117, v117
	v_mul_f32_e32 v118, 0xbfb8aa3b, v118
	v_exp_f32_e32 v104, v104
	v_mul_f32_e32 v105, 0xbfb8aa3b, v105
	v_exp_f32_e32 v118, v118
	v_exp_f32_e32 v105, v105
	v_add_f32_e32 v102, 1.0, v102
	v_rcp_f32_e32 v102, v102
	v_add_f32_e32 v103, 1.0, v103
	v_rcp_f32_e32 v116, v116
	v_add_f32_e32 v117, 1.0, v117
	v_rcp_f32_e32 v103, v103
	v_add_f32_e32 v104, 1.0, v104
	v_rcp_f32_e32 v117, v117
	v_add_f32_e32 v118, 1.0, v118
	v_rcp_f32_e32 v104, v104
	v_add_f32_e32 v105, 1.0, v105
	v_rcp_f32_e32 v118, v118
	v_rcp_f32_e32 v105, v105
	v_mul_f32_e32 v102, 0xbf1b4598, v102
	v_mul_f32_e32 v0, 0x3fb8aa3b, v0
	v_mul_f32_e32 v116, 0xbf1b4598, v116
	v_mul_f32_e32 v102, 0x3fb8aa3b, v102
	v_mul_f32_e32 v103, 0xbf1b4598, v103
	v_exp_f32_e32 v0, v0
	v_mul_f32_e32 v116, 0x3fb8aa3b, v116
	v_mul_f32_e32 v117, 0xbf1b4598, v117
	v_exp_f32_e32 v102, v102
	v_mul_f32_e32 v103, 0x3fb8aa3b, v103
	v_mul_f32_e32 v104, 0xbf1b4598, v104
	v_exp_f32_e32 v116, v116
	v_mul_f32_e32 v117, 0x3fb8aa3b, v117
	v_mul_f32_e32 v118, 0xbf1b4598, v118
	v_exp_f32_e32 v103, v103
	v_mul_f32_e32 v104, 0x3fb8aa3b, v104
	v_mul_f32_e32 v105, 0xbf1b4598, v105
	v_exp_f32_e32 v117, v117
	v_mul_f32_e32 v118, 0x3fb8aa3b, v118
	v_exp_f32_e32 v104, v104
	v_mul_f32_e32 v105, 0x3fb8aa3b, v105
	v_exp_f32_e32 v112, v118
	v_exp_f32_e32 v105, v105
	ds_write2_b32 v11, v0, v102 offset0:32 offset1:48
	ds_write2_b32 v11, v116, v103 offset0:96 offset1:112
	ds_write2_b32 v11, v117, v104 offset0:160 offset1:176
	ds_write2_b32 v11, v112, v105 offset0:224 offset1:240
.LBB0_1341:
	s_waitcnt vmcnt(0)
	s_add_i32 vcc_lo, s36, -1
	s_cmpk_gt_u32 vcc_lo, 0x3ff
	s_cbranch_scc1 .Lmy_w4_skR2
	v_perm_b32 v9, v199, v198, s42
	v_perm_b32 v10, v201, v200, s42
	v_perm_b32 v8, v202, v197, s42
	v_perm_b32 v7, v196, v203, s42
	v_perm_b32 v6, v204, v6, s42
.Lmy_w4_skR2:
	s_and_b64 vcc, exec, s[6:7]
	s_cbranch_vccnz .LBB0_1322
	s_add_i32 s10, s40, 16
	s_add_i32 s11, s41, -16
	s_and_b64 s[6:7], s[0:1], exec
	s_cselect_b32 s10, s10, s11
	s_cmp_eq_u32 s10, 0
	s_cselect_b64 s[6:7], -1, 0
	s_cmpk_lt_u32 s10, 0x3fff
	v_cndmask_b32_e64 v11, 1.0, 0, s[6:7]
	s_cselect_b64 s[6:7], -1, 0
	v_cndmask_b32_e64 v102, 0, 1.0, s[6:7]
	v_lshlrev_b32_e32 v104, 16, v5
	v_and_b32_e32 v103, 0xffff0000, v3
	v_mul_f32_e32 v104, v102, v104
	v_lshlrev_b32_e32 v0, 16, v2
	v_fmac_f32_e32 v104, v11, v103
	v_and_b32_e32 v105, 0xffff0000, v5
	v_fma_f32 v103, v104, 0.5, -v0
	v_lshlrev_b32_e32 v104, 16, v4
	v_mul_f32_e32 v105, v102, v105
	v_fmac_f32_e32 v0, v137, v103
	v_and_b32_e32 v103, 0xffff0000, v2
	v_fmac_f32_e32 v105, v11, v104
	v_lshlrev_b32_e32 v112, 16, v6
	v_fma_f32 v104, v105, 0.5, -v103
	v_and_b32_e32 v105, 0xffff0000, v4
	v_mul_f32_e32 v102, v102, v112
	v_fmac_f32_e32 v103, v138, v104
	v_lshlrev_b32_e32 v104, 16, v3
	v_fmac_f32_e32 v102, v11, v105
	v_fma_f32 v11, v102, 0.5, -v104
	v_mul_f32_e32 v102, v134, v103
	v_fmac_f32_e32 v104, v139, v11
	v_mul_f32_e32 v11, v102, v102
	v_mov_b32_e32 v112, 0
	ds_read_b32 v105, v145 offset:12288
	v_mov_b32_dpp v11, v11 quad_perm:[1,0,3,2] row_mask:0xf bank_mask:0xf bound_ctrl:1
	v_fmac_f32_e32 v11, v102, v102
	s_and_b64 vcc, exec, s[8:9]
	s_nop 0
	v_add_f32_dpp v11, v11, v11 quad_perm:[2,3,0,1] row_mask:0xf bank_mask:0xf bound_ctrl:1
	s_nop 1
	v_add_f32_dpp v11, v11, v11 row_half_mirror row_mask:0xf bank_mask:0xf bound_ctrl:1
	s_nop 1
	v_add_f32_dpp v11, v11, v11 row_mirror row_mask:0xf bank_mask:0xf bound_ctrl:1
	s_nop 1
	v_mov_b32_dpp v112, v11 row_bcast:15 row_mask:0xa bank_mask:0xf
	v_add_f32_e32 v11, v11, v112
	v_mov_b32_e32 v112, 0
	s_nop 1
	v_mov_b32_dpp v112, v11 row_bcast:31 row_mask:0xc bank_mask:0xf
	v_add_f32_e32 v11, v11, v112
	s_nop 0
	v_readlane_b32 s6, v11, 63
	s_nop 1
	v_max_f32_e64 v11, s6, s6
	v_max_f32_e32 v11, 0x179abe15, v11
	v_rsq_f32_e32 v112, v11
	s_waitcnt lgkmcnt(0)
	v_add_f32_e32 v11, -1.0, v105
	v_fma_f32 v11, v135, v11, 1.0
	v_mul_f32_e32 v11, v103, v11
	v_mul_f32_e32 v102, v102, v112
	v_mul_f32_e32 v103, v105, v102
	ds_write2st64_b32 v145, v102, v103 offset0:80 offset1:81
	ds_write2st64_b32 v145, v11, v0 offset0:82 offset1:83
	ds_write_b32 v145, v104 offset:21504
	s_cbranch_vccnz .LBB0_1322
	v_mul_f32_e32 v0, v0, v11
	v_mul_f32_e32 v11, v136, v0
	s_nop 1
	v_mov_b32_dpp v11, v11 quad_perm:[1,0,3,2] row_mask:0xf bank_mask:0xf bound_ctrl:1
	v_fmac_f32_e32 v11, v136, v0
	s_nop 1
	v_add_f32_dpp v0, v11, v11 quad_perm:[2,3,0,1] row_mask:0xf bank_mask:0xf bound_ctrl:1
	v_mov_b32_e32 v11, 0
	s_nop 0
	v_add_f32_dpp v0, v0, v0 row_half_mirror row_mask:0xf bank_mask:0xf bound_ctrl:1
	s_nop 1
	v_add_f32_dpp v0, v0, v0 row_mirror row_mask:0xf bank_mask:0xf bound_ctrl:1
	s_nop 1
	v_mov_b32_dpp v11, v0 row_bcast:15 row_mask:0xa bank_mask:0xf
	v_add_f32_e32 v0, v0, v11
	v_mov_b32_e32 v11, 0
	s_nop 1
	v_mov_b32_dpp v11, v0 row_bcast:31 row_mask:0xc bank_mask:0xf
	v_add_f32_e32 v0, v0, v11
	s_nop 0
	v_readlane_b32 s8, v0, 63
	s_and_saveexec_b64 s[6:7], s[4:5]
	s_cbranch_execz .LBB0_1321
	s_lshl_b32 s9, s10, 7
	s_add_i32 s9, s9, s60
	v_mov_b32_e32 v0, s9
	v_mov_b32_e32 v11, s8
	global_store_dword v0, v11, s[24:25]
	s_branch .LBB0_1321
